# GU: last K iteration peeled with the ai=0 half of the SwiGLU epilogue interleaved into its final MFMA block; rstd cached in registers; C=0 first touch
# baseline (speedup 1.0000x reference)
; #define PG8_STAGE(bufoff, gbase, voff) do { _Pragma("unroll") for (int _i = 0; _i < 2; ++_i) \
;         __builtin_amdgcn_global_load_lds((const unsigned*)((const char*)(gbase) + (voff)[_i]), (LAS unsigned*)(lds + (bufoff) + ldsw + _i * 8192), 16, 0, 0); } while (0)
; #define PG8_LDA(dst, b, h) do { _Pragma("unroll") for (int m = 0; m < 4; ++m) _Pragma("unroll") for (int k = 0; k < 2; ++k) dst[m][k] = *(const LAS bf16x8*)(lds + PG8_SA(b, h) + aoff + m * 2048 + k * 1024); } while (0)
; #define PG8_LDB(dst, b, h) do { _Pragma("unroll") for (int n = 0; n < 2; ++n) _Pragma("unroll") for (int k = 0; k < 2; ++k) dst[n][k] = *(const LAS bf16x8*)(lds + PG8_SB(b, h) + boff + n * 2048 + k * 1024); } while (0)
; #define PG8_MMA(ai, bj, At, Bt) do { __builtin_amdgcn_s_setprio(1); _Pragma("unroll") for (int k = 0; k < 2; ++k) _Pragma("unroll") for (int m = 0; m < 4; ++m) _Pragma("unroll") for (int n = 0; n < 2; ++n) \
;         acc[ai][bj][m][n] = __builtin_amdgcn_mfma_f32_16x16x32_bf16(Bt[n][k], At[m][k], acc[ai][bj][m][n], 0, 0, 0); __builtin_amdgcn_s_setprio(0); } while (0)
; #define PG8_WAIT_V(n) asm volatile("s_waitcnt vmcnt(" #n ")" ::: "memory")
; #define PG8_WAIT_L(n) asm volatile("s_waitcnt lgkmcnt(" #n ")" ::: "memory")
; #define PG8_BAR __builtin_amdgcn_s_barrier()
; #define PG8_SCHED __builtin_amdgcn_sched_barrier(0)
; __device__ __forceinline__ void load_rstd(float (&rsv)[2][4], const ssq_t* ssq, int row0) {
;     ssq_t t[2][4];
; #pragma unroll
;     for (int ai = 0; ai < 2; ++ai)
; #pragma unroll
;         for (int m = 0; m < 4; ++m) t[ai][m] = ssq[row0 + ai * HALF + m * 16];
; #pragma unroll
;     for (int ai = 0; ai < 2; ++ai)
; #pragma unroll
;         for (int m = 0; m < 4; ++m) rsv[ai][m] = __builtin_amdgcn_rsqf((float)t[ai][m] * (SSQ_INV / 1024.0f) + 1e-6f);
; }
; template <class Epi, bool ALIGN_EPI>
; __device__ __forceinline__ void gemm_phase(LAS unsigned char* lds, const Gemm g, const StaticOrder& S, const Epi& E, const int tid) {
;     ...
;             PG8_LDB(B0, 0, 0); PG8_LDB(B1, 0, 1); PG8_SCHED; PG8_LDA(At, 0, 0); PG8_STAGE(PG8_SA(1, 1), a1 + hA, voffA);
;             PG8_WAIT_V(8); PG8_WAIT_L(0); PG8_BAR; PG8_MMA(0, 0, At, B0); PG8_MMA(0, 1, At, B1); PG8_BAR; PG8_SCHED;
.LBB0_306:
	s_andn2_b64 vcc, exec, s[36:37]
	s_cbranch_vccnz .LBB0_309
	v_lshl_add_u64 v[142:143], v[142:143], 0, s[92:93]
	v_lshl_add_u64 v[144:145], v[144:145], 0, s[80:81]
	s_mov_b32 s10, 0
	v_readfirstlane_b32 s98, v254
	s_cmp_eq_u32 s98, s64
	s_cbranch_scc1 .Lgu_rs_ok
	v_lshrrev_b32_e32 v194, 8, v170
	v_and_b32_e32 v195, 15, v170
	v_lshl_add_u32 v194, v194, 6, v195
	s_lshl_b32 s98, s64, 8
	v_add_u32_e32 v194, s98, v194
	v_lshlrev_b32_e32 v192, 3, v194
	v_mov_b32_e32 v193, 0
	v_lshl_add_u64 v[192:193], v[192:193], 0, s[26:27]
	global_load_dwordx2 v[176:177], v[192:193], off
	global_load_dwordx2 v[178:179], v[192:193], off offset:128
	global_load_dwordx2 v[180:181], v[192:193], off offset:256
	global_load_dwordx2 v[182:183], v[192:193], off offset:384
	global_load_dwordx2 v[184:185], v[192:193], off offset:1024
	global_load_dwordx2 v[186:187], v[192:193], off offset:1152
	global_load_dwordx2 v[188:189], v[192:193], off offset:1280
	global_load_dwordx2 v[190:191], v[192:193], off offset:1408
	s_waitcnt vmcnt(0)
	v_ffbh_u32_e32 v194, v177
	v_min_u32_e32 v194, 32, v194
	v_lshlrev_b64 v[176:177], v194, v[176:177]
	v_min_u32_e32 v176, 1, v176
	v_or_b32_e32 v176, v177, v176
	v_cvt_f32_u32_e32 v176, v176
	v_sub_u32_e32 v194, 32, v194
	v_ldexp_f32 v176, v176, v194
	v_fmamk_f32 v176, v176, 0x30800000, v223
	v_rsq_f32_e32 v176, v176
	v_ffbh_u32_e32 v194, v179
	v_min_u32_e32 v194, 32, v194
	v_lshlrev_b64 v[178:179], v194, v[178:179]
	v_min_u32_e32 v178, 1, v178
	v_or_b32_e32 v178, v179, v178
	v_cvt_f32_u32_e32 v178, v178
	v_sub_u32_e32 v194, 32, v194
	v_ldexp_f32 v178, v178, v194
	v_fmamk_f32 v178, v178, 0x30800000, v223
	v_rsq_f32_e32 v178, v178
	v_ffbh_u32_e32 v194, v181
	v_min_u32_e32 v194, 32, v194
	v_lshlrev_b64 v[180:181], v194, v[180:181]
	v_min_u32_e32 v180, 1, v180
	v_or_b32_e32 v180, v181, v180
	v_cvt_f32_u32_e32 v180, v180
	v_sub_u32_e32 v194, 32, v194
	v_ldexp_f32 v180, v180, v194
	v_fmamk_f32 v180, v180, 0x30800000, v223
	v_rsq_f32_e32 v180, v180
	v_ffbh_u32_e32 v194, v183
	v_min_u32_e32 v194, 32, v194
	v_lshlrev_b64 v[182:183], v194, v[182:183]
	v_min_u32_e32 v182, 1, v182
	v_or_b32_e32 v182, v183, v182
	v_cvt_f32_u32_e32 v182, v182
	v_sub_u32_e32 v194, 32, v194
	v_ldexp_f32 v182, v182, v194
	v_fmamk_f32 v182, v182, 0x30800000, v223
	v_rsq_f32_e32 v182, v182
	v_ffbh_u32_e32 v194, v185
	v_min_u32_e32 v194, 32, v194
	v_lshlrev_b64 v[184:185], v194, v[184:185]
	v_min_u32_e32 v184, 1, v184
	v_or_b32_e32 v184, v185, v184
	v_cvt_f32_u32_e32 v184, v184
	v_sub_u32_e32 v194, 32, v194
	v_ldexp_f32 v184, v184, v194
	v_fmamk_f32 v184, v184, 0x30800000, v223
	v_rsq_f32_e32 v184, v184
	v_ffbh_u32_e32 v194, v187
	v_min_u32_e32 v194, 32, v194
	v_lshlrev_b64 v[186:187], v194, v[186:187]
	v_min_u32_e32 v186, 1, v186
	v_or_b32_e32 v186, v187, v186
	v_cvt_f32_u32_e32 v186, v186
	v_sub_u32_e32 v194, 32, v194
	v_ldexp_f32 v186, v186, v194
	v_fmamk_f32 v186, v186, 0x30800000, v223
	v_rsq_f32_e32 v186, v186
	v_ffbh_u32_e32 v194, v189
	v_min_u32_e32 v194, 32, v194
	v_lshlrev_b64 v[188:189], v194, v[188:189]
	v_min_u32_e32 v188, 1, v188
	v_or_b32_e32 v188, v189, v188
	v_cvt_f32_u32_e32 v188, v188
	v_sub_u32_e32 v194, 32, v194
	v_ldexp_f32 v188, v188, v194
	v_fmamk_f32 v188, v188, 0x30800000, v223
	v_rsq_f32_e32 v188, v188
	v_ffbh_u32_e32 v194, v191
	v_min_u32_e32 v194, 32, v194
	v_lshlrev_b64 v[190:191], v194, v[190:191]
	v_min_u32_e32 v190, 1, v190
	v_or_b32_e32 v190, v191, v190
	v_cvt_f32_u32_e32 v190, v190
	v_sub_u32_e32 v194, 32, v194
	v_ldexp_f32 v190, v190, v194
	v_fmamk_f32 v190, v190, 0x30800000, v223
	v_rsq_f32_e32 v190, v190
	v_mov_b32_e32 v172, v176
	v_mov_b32_e32 v173, v178
	v_mov_b32_e32 v236, v180
	v_mov_b32_e32 v237, v182
	v_mov_b32_e32 v238, v184
	v_mov_b32_e32 v239, v186
	v_mov_b32_e32 v230, v188
	v_mov_b32_e32 v231, v190
	v_mov_b32_e32 v254, s64
.Lgu_rs_ok:
.Lgu_first:
	s_add_i32 s11, s10, 2
	s_cmp_eq_u32 s58, s10
	v_lshl_add_u64 v[146:147], v[142:143], 0, s[92:93]
	s_cselect_b64 vcc, -1, 0
	v_add_u32_e32 v150, s33, v151
	s_add_i32 s10, 0, 0x14000
	v_cndmask_b32_e32 v167, v147, v139, vcc
	v_cndmask_b32_e32 v166, v146, v138, vcc
	ds_read_b128 v[146:149], v150
	ds_read_b128 v[154:157], v150 offset:1024
	ds_read_b128 v[158:161], v150 offset:2048
	ds_read_b128 v[162:165], v150 offset:3072
	v_add_u32_e32 v150, s10, v151
	ds_read_b128 v[176:179], v150
	ds_read_b128 v[180:183], v150 offset:1024
	ds_read_b128 v[184:187], v150 offset:2048
	ds_read_b128 v[188:191], v150 offset:3072
	v_cndmask_b32_e32 v221, v145, v141, vcc
	v_cndmask_b32_e32 v220, v144, v140, vcc
	v_lshl_add_u64 v[226:227], v[142:143], 0, v[134:135]
	s_add_i32 m0, s51, 0xc000
	ds_read_b128 v[192:195], v153
	ds_read_b128 v[196:199], v153 offset:1024
	ds_read_b128 v[200:203], v153 offset:2048
	ds_read_b128 v[204:207], v153 offset:3072
	ds_read_b128 v[208:211], v153 offset:4096
	ds_read_b128 v[212:215], v153 offset:5120
	ds_read_b128 v[216:219], v153 offset:6144
	ds_read_b128 v[240:243], v153 offset:7168
	global_load_lds_dwordx4 v[226:227], off
	v_lshl_add_u64 v[226:227], v[142:143], 0, v[136:137]
	s_add_i32 m0, s51, 0xe000
	s_nop 0
	global_load_lds_dwordx4 v[226:227], off
	s_waitcnt vmcnt(8)
	s_waitcnt lgkmcnt(0)
	s_barrier
; #define PG8_STAGE(bufoff, gbase, voff) do { _Pragma("unroll") for (int _i = 0; _i < 2; ++_i) \
;         __builtin_amdgcn_global_load_lds((const unsigned*)((const char*)(gbase) + (voff)[_i]), (LAS unsigned*)(lds + (bufoff) + ldsw + _i * 8192), 16, 0, 0); } while (0)
; #define PG8_LDA(dst, b, h) do { _Pragma("unroll") for (int m = 0; m < 4; ++m) _Pragma("unroll") for (int k = 0; k < 2; ++k) dst[m][k] = *(const LAS bf16x8*)(lds + PG8_SA(b, h) + aoff + m * 2048 + k * 1024); } while (0)
; #define PG8_MMA(ai, bj, At, Bt) do { __builtin_amdgcn_s_setprio(1); _Pragma("unroll") for (int k = 0; k < 2; ++k) _Pragma("unroll") for (int m = 0; m < 4; ++m) _Pragma("unroll") for (int n = 0; n < 2; ++n) \
;         acc[ai][bj][m][n] = __builtin_amdgcn_mfma_f32_16x16x32_bf16(Bt[n][k], At[m][k], acc[ai][bj][m][n], 0, 0, 0); __builtin_amdgcn_s_setprio(0); } while (0)
; #define PG8_WAIT_V(n) asm volatile("s_waitcnt vmcnt(" #n ")" ::: "memory")
; #define PG8_WAIT_L(n) asm volatile("s_waitcnt lgkmcnt(" #n ")" ::: "memory")
; #define PG8_BAR __builtin_amdgcn_s_barrier()
; #define PG8_SCHED __builtin_amdgcn_sched_barrier(0)
; template <class Epi, bool ALIGN_EPI>
; __device__ __forceinline__ void gemm_phase(LAS unsigned char* lds, const Gemm g, const StaticOrder& S, const Epi& E, const int tid) {
;     ...
;             PG8_WAIT_V(8); PG8_WAIT_L(0); PG8_BAR; PG8_MMA(0, 0, At, B0); PG8_MMA(0, 1, At, B1); PG8_BAR; PG8_SCHED;
;             PG8_LDA(At, 0, 1); PG8_STAGE(PG8_SB(0, 0), b2, voffB); PG8_STAGE(PG8_SB(0, 1), b2 + hB, voffB); PG8_STAGE(PG8_SA(0, 0), a2, voffA);
;             PG8_WAIT_V(8); PG8_WAIT_L(0); PG8_BAR; PG8_MMA(1, 0, At, B0); PG8_MMA(1, 1, At, B1); PG8_BAR; PG8_SCHED;
	s_setprio 1
	s_waitcnt lgkmcnt(0)
	v_mfma_f32_16x16x32_bf16 v[120:123], v[146:149], v[192:195], 0
	v_mfma_f32_16x16x32_bf16 v[112:115], v[158:161], v[192:195], 0
	v_mfma_f32_16x16x32_bf16 v[104:107], v[146:149], v[200:203], 0
	v_mfma_f32_16x16x32_bf16 v[96:99], v[158:161], v[200:203], 0
	v_mfma_f32_16x16x32_bf16 v[88:91], v[146:149], v[208:211], 0
	v_mfma_f32_16x16x32_bf16 v[80:83], v[158:161], v[208:211], 0
	v_mfma_f32_16x16x32_bf16 v[72:75], v[146:149], v[216:219], 0
	v_mfma_f32_16x16x32_bf16 v[64:67], v[158:161], v[216:219], 0
	v_mfma_f32_16x16x32_bf16 v[120:123], v[154:157], v[196:199], v[120:123]
	v_mfma_f32_16x16x32_bf16 v[112:115], v[162:165], v[196:199], v[112:115]
	v_mfma_f32_16x16x32_bf16 v[104:107], v[154:157], v[204:207], v[104:107]
	v_mfma_f32_16x16x32_bf16 v[96:99], v[162:165], v[204:207], v[96:99]
	v_mfma_f32_16x16x32_bf16 v[88:91], v[154:157], v[212:215], v[88:91]
	v_mfma_f32_16x16x32_bf16 v[80:83], v[162:165], v[212:215], v[80:83]
	v_mfma_f32_16x16x32_bf16 v[72:75], v[154:157], v[240:243], v[72:75]
	v_mfma_f32_16x16x32_bf16 v[64:67], v[162:165], v[240:243], v[64:67]
	s_setprio 0
	s_setprio 1
	v_mfma_f32_16x16x32_bf16 v[124:127], v[176:179], v[192:195], 0
	v_mfma_f32_16x16x32_bf16 v[116:119], v[184:187], v[192:195], 0
	v_mfma_f32_16x16x32_bf16 v[108:111], v[176:179], v[200:203], 0
	v_mfma_f32_16x16x32_bf16 v[100:103], v[184:187], v[200:203], 0
	v_mfma_f32_16x16x32_bf16 v[92:95], v[176:179], v[208:211], 0
	v_mfma_f32_16x16x32_bf16 v[84:87], v[184:187], v[208:211], 0
	v_mfma_f32_16x16x32_bf16 v[76:79], v[176:179], v[216:219], 0
	v_mfma_f32_16x16x32_bf16 v[68:71], v[184:187], v[216:219], 0
	v_mfma_f32_16x16x32_bf16 v[124:127], v[180:183], v[196:199], v[124:127]
	v_mfma_f32_16x16x32_bf16 v[116:119], v[188:191], v[196:199], v[116:119]
	v_mfma_f32_16x16x32_bf16 v[108:111], v[180:183], v[204:207], v[108:111]
	v_mfma_f32_16x16x32_bf16 v[100:103], v[188:191], v[204:207], v[100:103]
	v_mfma_f32_16x16x32_bf16 v[92:95], v[180:183], v[212:215], v[92:95]
	v_mfma_f32_16x16x32_bf16 v[84:87], v[188:191], v[212:215], v[84:87]
	v_mfma_f32_16x16x32_bf16 v[76:79], v[180:183], v[240:243], v[76:79]
	v_mfma_f32_16x16x32_bf16 v[68:71], v[188:191], v[240:243], v[68:71]
	s_setprio 0
	s_barrier
	s_add_i32 s65, s33, s45
	v_lshl_add_u64 v[226:227], v[220:221], 0, v[168:169]
	s_mov_b32 m0, s65
	ds_read_b128 v[192:195], v153 offset:16384
	ds_read_b128 v[196:199], v153 offset:17408
	ds_read_b128 v[200:203], v153 offset:18432
	ds_read_b128 v[204:207], v153 offset:19456
	ds_read_b128 v[208:211], v153 offset:20480
	ds_read_b128 v[212:215], v153 offset:21504
	ds_read_b128 v[216:219], v153 offset:22528
	ds_read_b128 v[240:243], v153 offset:23552
	global_load_lds_dwordx4 v[226:227], off
	v_lshl_add_u64 v[244:245], v[220:221], 0, v[128:129]
	s_add_i32 m0, s65, 0x2000
	v_lshl_add_u64 v[220:221], v[220:221], 0, s[12:13]
	s_add_i32 s10, s10, s45
	global_load_lds_dwordx4 v[244:245], off
	v_lshl_add_u64 v[246:247], v[220:221], 0, v[168:169]
	s_mov_b32 m0, s10
	v_lshl_add_u64 v[220:221], v[220:221], 0, v[128:129]
	global_load_lds_dwordx4 v[246:247], off
	s_add_i32 m0, s10, 0x2000
	v_lshl_add_u64 v[248:249], v[166:167], 0, v[132:133]
	global_load_lds_dwordx4 v[220:221], off
	s_mov_b32 m0, s51
	v_lshl_add_u64 v[250:251], v[166:167], 0, v[130:131]
	global_load_lds_dwordx4 v[248:249], off
	s_mov_b32 m0, s52
	s_nop 0
	global_load_lds_dwordx4 v[250:251], off
	s_waitcnt vmcnt(8)
	s_waitcnt lgkmcnt(0)
	s_barrier
	s_setprio 1
	s_waitcnt lgkmcnt(0)
	v_mfma_f32_16x16x32_bf16 v[56:59], v[146:149], v[192:195], 0
	v_mfma_f32_16x16x32_bf16 v[48:51], v[158:161], v[192:195], 0
	v_mfma_f32_16x16x32_bf16 v[40:43], v[146:149], v[200:203], 0
	v_mfma_f32_16x16x32_bf16 v[32:35], v[158:161], v[200:203], 0
	v_mfma_f32_16x16x32_bf16 v[24:27], v[146:149], v[208:211], 0
	v_mfma_f32_16x16x32_bf16 v[16:19], v[158:161], v[208:211], 0
	v_mfma_f32_16x16x32_bf16 v[8:11], v[146:149], v[216:219], 0
	v_mfma_f32_16x16x32_bf16 v[4:7], v[158:161], v[216:219], 0
	v_mfma_f32_16x16x32_bf16 v[56:59], v[154:157], v[196:199], v[56:59]
	v_mfma_f32_16x16x32_bf16 v[48:51], v[162:165], v[196:199], v[48:51]
	v_mfma_f32_16x16x32_bf16 v[40:43], v[154:157], v[204:207], v[40:43]
	v_mfma_f32_16x16x32_bf16 v[32:35], v[162:165], v[204:207], v[32:35]
	v_mfma_f32_16x16x32_bf16 v[24:27], v[154:157], v[212:215], v[24:27]
	v_mfma_f32_16x16x32_bf16 v[16:19], v[162:165], v[212:215], v[16:19]
	v_mfma_f32_16x16x32_bf16 v[8:11], v[154:157], v[240:243], v[8:11]
	v_mfma_f32_16x16x32_bf16 v[4:7], v[162:165], v[240:243], v[4:7]
	s_setprio 0
	s_setprio 1
	v_mfma_f32_16x16x32_bf16 v[60:63], v[176:179], v[192:195], 0
	v_mfma_f32_16x16x32_bf16 v[52:55], v[184:187], v[192:195], 0
	v_mfma_f32_16x16x32_bf16 v[44:47], v[176:179], v[200:203], 0
	v_mfma_f32_16x16x32_bf16 v[36:39], v[184:187], v[200:203], 0
	v_mfma_f32_16x16x32_bf16 v[28:31], v[176:179], v[208:211], 0
	v_mfma_f32_16x16x32_bf16 v[20:23], v[184:187], v[208:211], 0
	v_mfma_f32_16x16x32_bf16 v[12:15], v[176:179], v[216:219], 0
	v_mfma_f32_16x16x32_bf16 v[0:3], v[184:187], v[216:219], 0
	v_mfma_f32_16x16x32_bf16 v[60:63], v[180:183], v[196:199], v[60:63]
	v_mfma_f32_16x16x32_bf16 v[52:55], v[188:191], v[196:199], v[52:55]
	v_mfma_f32_16x16x32_bf16 v[44:47], v[180:183], v[204:207], v[44:47]
	v_mfma_f32_16x16x32_bf16 v[36:39], v[188:191], v[204:207], v[36:39]
	v_mfma_f32_16x16x32_bf16 v[28:31], v[180:183], v[212:215], v[28:31]
	v_mfma_f32_16x16x32_bf16 v[20:23], v[188:191], v[212:215], v[20:23]
	v_mfma_f32_16x16x32_bf16 v[12:15], v[180:183], v[240:243], v[12:15]
	v_mfma_f32_16x16x32_bf16 v[0:3], v[188:191], v[240:243], v[0:3]
	s_setprio 0
	s_barrier
; #define PG8_STAGE(bufoff, gbase, voff) do { _Pragma("unroll") for (int _i = 0; _i < 2; ++_i) \
;         __builtin_amdgcn_global_load_lds((const unsigned*)((const char*)(gbase) + (voff)[_i]), (LAS unsigned*)(lds + (bufoff) + ldsw + _i * 8192), 16, 0, 0); } while (0)
; #define PG8_LDA(dst, b, h) do { _Pragma("unroll") for (int m = 0; m < 4; ++m) _Pragma("unroll") for (int k = 0; k < 2; ++k) dst[m][k] = *(const LAS bf16x8*)(lds + PG8_SA(b, h) + aoff + m * 2048 + k * 1024); } while (0)
; #define PG8_LDB(dst, b, h) do { _Pragma("unroll") for (int n = 0; n < 2; ++n) _Pragma("unroll") for (int k = 0; k < 2; ++k) dst[n][k] = *(const LAS bf16x8*)(lds + PG8_SB(b, h) + boff + n * 2048 + k * 1024); } while (0)
; #define PG8_MMA(ai, bj, At, Bt) do { __builtin_amdgcn_s_setprio(1); _Pragma("unroll") for (int k = 0; k < 2; ++k) _Pragma("unroll") for (int m = 0; m < 4; ++m) _Pragma("unroll") for (int n = 0; n < 2; ++n) \
;         acc[ai][bj][m][n] = __builtin_amdgcn_mfma_f32_16x16x32_bf16(Bt[n][k], At[m][k], acc[ai][bj][m][n], 0, 0, 0); __builtin_amdgcn_s_setprio(0); } while (0)
; #define PG8_WAIT_V(n) asm volatile("s_waitcnt vmcnt(" #n ")" ::: "memory")
; #define PG8_WAIT_L(n) asm volatile("s_waitcnt lgkmcnt(" #n ")" ::: "memory")
; #define PG8_BAR __builtin_amdgcn_s_barrier()
; #define PG8_SCHED __builtin_amdgcn_sched_barrier(0)
; template <class Epi, bool ALIGN_EPI>
; __device__ __forceinline__ void gemm_phase(LAS unsigned char* lds, const Gemm g, const StaticOrder& S, const Epi& E, const int tid) {
;     ...
;             PG8_LDB(B0, 1, 0); PG8_LDB(B1, 1, 1); PG8_SCHED; PG8_LDA(At, 1, 0); PG8_STAGE(PG8_SA(0, 1), a2 + hA, voffA);
;             PG8_WAIT_V(8); PG8_WAIT_L(0); PG8_BAR; PG8_MMA(0, 0, At, B0); PG8_MMA(0, 1, At, B1); PG8_BAR; PG8_SCHED;
;             PG8_LDA(At, 1, 1); PG8_STAGE(PG8_SB(1, 0), b3, voffB); PG8_STAGE(PG8_SB(1, 1), b3 + hB, voffB); PG8_STAGE(PG8_SA(1, 0), a3, voffA);
;             PG8_WAIT_V(8); PG8_WAIT_L(0); PG8_BAR; PG8_MMA(1, 0, At, B0); PG8_MMA(1, 1, At, B1); PG8_BAR; PG8_SCHED;
	s_add_i32 s10, 0, 0x18000
	v_add_u32_e32 v150, s10, v151
	s_add_i32 s65, 0, 0x1c000
	ds_read_b128 v[146:149], v150
	ds_read_b128 v[154:157], v150 offset:1024
	ds_read_b128 v[158:161], v150 offset:2048
	ds_read_b128 v[162:165], v150 offset:3072
	v_add_u32_e32 v150, s65, v151
	ds_read_b128 v[176:179], v150
	ds_read_b128 v[180:183], v150 offset:1024
	ds_read_b128 v[184:187], v150 offset:2048
	ds_read_b128 v[188:191], v150 offset:3072
	v_lshl_add_u64 v[166:167], v[166:167], 0, s[94:95]
	s_mov_b32 m0, s53
	v_lshl_add_u64 v[252:253], v[166:167], 0, v[132:133]
	ds_read_b128 v[192:195], v153 offset:32768
	ds_read_b128 v[196:199], v153 offset:33792
	ds_read_b128 v[200:203], v153 offset:34816
	ds_read_b128 v[204:207], v153 offset:35840
	ds_read_b128 v[208:211], v153 offset:36864
	ds_read_b128 v[212:215], v153 offset:37888
	ds_read_b128 v[216:219], v153 offset:38912
	ds_read_b128 v[240:243], v153 offset:39936
	global_load_lds_dwordx4 v[252:253], off
	v_lshl_add_u64 v[166:167], v[166:167], 0, v[130:131]
	s_mov_b32 m0, s54
	s_nop 0
	global_load_lds_dwordx4 v[166:167], off
	s_waitcnt vmcnt(8)
	s_waitcnt lgkmcnt(0)
	s_barrier
	s_setprio 1
	s_waitcnt lgkmcnt(0)
	v_mfma_f32_16x16x32_bf16 v[120:123], v[146:149], v[192:195], v[120:123]
	v_mfma_f32_16x16x32_bf16 v[112:115], v[158:161], v[192:195], v[112:115]
	v_mfma_f32_16x16x32_bf16 v[104:107], v[146:149], v[200:203], v[104:107]
	v_mfma_f32_16x16x32_bf16 v[96:99], v[158:161], v[200:203], v[96:99]
	v_mfma_f32_16x16x32_bf16 v[88:91], v[146:149], v[208:211], v[88:91]
	v_mfma_f32_16x16x32_bf16 v[80:83], v[158:161], v[208:211], v[80:83]
	v_mfma_f32_16x16x32_bf16 v[72:75], v[146:149], v[216:219], v[72:75]
	v_mfma_f32_16x16x32_bf16 v[64:67], v[158:161], v[216:219], v[64:67]
	v_mfma_f32_16x16x32_bf16 v[120:123], v[154:157], v[196:199], v[120:123]
	v_mfma_f32_16x16x32_bf16 v[112:115], v[162:165], v[196:199], v[112:115]
	v_mfma_f32_16x16x32_bf16 v[104:107], v[154:157], v[204:207], v[104:107]
	v_mfma_f32_16x16x32_bf16 v[96:99], v[162:165], v[204:207], v[96:99]
	v_mfma_f32_16x16x32_bf16 v[88:91], v[154:157], v[212:215], v[88:91]
	v_mfma_f32_16x16x32_bf16 v[80:83], v[162:165], v[212:215], v[80:83]
	v_mfma_f32_16x16x32_bf16 v[72:75], v[154:157], v[240:243], v[72:75]
	v_mfma_f32_16x16x32_bf16 v[64:67], v[162:165], v[240:243], v[64:67]
	s_setprio 0
	s_setprio 1
	v_mfma_f32_16x16x32_bf16 v[124:127], v[176:179], v[192:195], v[124:127]
	v_mfma_f32_16x16x32_bf16 v[116:119], v[184:187], v[192:195], v[116:119]
	v_mfma_f32_16x16x32_bf16 v[108:111], v[176:179], v[200:203], v[108:111]
	v_mfma_f32_16x16x32_bf16 v[100:103], v[184:187], v[200:203], v[100:103]
	v_mfma_f32_16x16x32_bf16 v[92:95], v[176:179], v[208:211], v[92:95]
	v_mfma_f32_16x16x32_bf16 v[84:87], v[184:187], v[208:211], v[84:87]
	v_mfma_f32_16x16x32_bf16 v[76:79], v[176:179], v[216:219], v[76:79]
	v_mfma_f32_16x16x32_bf16 v[68:71], v[184:187], v[216:219], v[68:71]
	v_mfma_f32_16x16x32_bf16 v[124:127], v[180:183], v[196:199], v[124:127]
	v_mfma_f32_16x16x32_bf16 v[116:119], v[188:191], v[196:199], v[116:119]
	v_mfma_f32_16x16x32_bf16 v[108:111], v[180:183], v[204:207], v[108:111]
	v_mfma_f32_16x16x32_bf16 v[100:103], v[188:191], v[204:207], v[100:103]
	v_mfma_f32_16x16x32_bf16 v[92:95], v[180:183], v[212:215], v[92:95]
	v_mfma_f32_16x16x32_bf16 v[84:87], v[188:191], v[212:215], v[84:87]
	v_mfma_f32_16x16x32_bf16 v[76:79], v[180:183], v[240:243], v[76:79]
	v_mfma_f32_16x16x32_bf16 v[68:71], v[188:191], v[240:243], v[68:71]
	s_setprio 0
	s_barrier
	s_add_i32 s10, s10, s45
	v_lshl_add_u64 v[166:167], v[226:227], 0, s[92:93]
	s_mov_b32 m0, s10
	ds_read_b128 v[192:195], v153 offset:49152
	ds_read_b128 v[196:199], v153 offset:50176
	ds_read_b128 v[200:203], v153 offset:51200
	ds_read_b128 v[204:207], v153 offset:52224
	ds_read_b128 v[208:211], v153 offset:53248
	ds_read_b128 v[212:215], v153 offset:54272
	ds_read_b128 v[216:219], v153 offset:55296
	ds_read_b128 v[240:243], v153 offset:56320
	global_load_lds_dwordx4 v[166:167], off
	v_lshl_add_u64 v[166:167], v[244:245], 0, s[92:93]
	s_add_i32 m0, s10, 0x2000
	s_add_i32 s10, s65, s45
	global_load_lds_dwordx4 v[166:167], off
	v_lshl_add_u64 v[166:167], v[246:247], 0, s[92:93]
	s_mov_b32 m0, s10
	s_nop 0
	global_load_lds_dwordx4 v[166:167], off
	v_lshl_add_u64 v[166:167], v[220:221], 0, s[92:93]
	s_add_i32 m0, s10, 0x2000
	s_nop 0
	global_load_lds_dwordx4 v[166:167], off
	v_lshl_add_u64 v[166:167], v[248:249], 0, s[92:93]
	s_mov_b32 m0, s56
	s_nop 0
	global_load_lds_dwordx4 v[166:167], off
	v_lshl_add_u64 v[166:167], v[250:251], 0, s[92:93]
	s_mov_b32 m0, s57
	s_nop 0
	global_load_lds_dwordx4 v[166:167], off
	s_waitcnt vmcnt(8)
	s_waitcnt lgkmcnt(0)
	s_barrier
; #define PG8_STAGE(bufoff, gbase, voff) do { _Pragma("unroll") for (int _i = 0; _i < 2; ++_i) \
;         __builtin_amdgcn_global_load_lds((const unsigned*)((const char*)(gbase) + (voff)[_i]), (LAS unsigned*)(lds + (bufoff) + ldsw + _i * 8192), 16, 0, 0); } while (0)
; #define PG8_LDA(dst, b, h) do { _Pragma("unroll") for (int m = 0; m < 4; ++m) _Pragma("unroll") for (int k = 0; k < 2; ++k) dst[m][k] = *(const LAS bf16x8*)(lds + PG8_SA(b, h) + aoff + m * 2048 + k * 1024); } while (0)
; #define PG8_LDB(dst, b, h) do { _Pragma("unroll") for (int n = 0; n < 2; ++n) _Pragma("unroll") for (int k = 0; k < 2; ++k) dst[n][k] = *(const LAS bf16x8*)(lds + PG8_SB(b, h) + boff + n * 2048 + k * 1024); } while (0)
; #define PG8_WAIT_V(n) asm volatile("s_waitcnt vmcnt(" #n ")" ::: "memory")
; #define PG8_BAR __builtin_amdgcn_s_barrier()
; template <class Epi, bool ALIGN_EPI>
; __device__ __forceinline__ void gemm_phase(LAS unsigned char* lds, const Gemm g, const StaticOrder& S, const Epi& E, const int tid) {
;     ...
;         for (int t = 0; t < nt; t += 2) {
;             const bool last = (t == nt - 2);
;             const char* a1 = cA + (size_t)(t + 1) * kstep;
;             const char* a2 = last ? nA : cA + (size_t)(t + 2) * kstep; const char* b2 = last ? nB : cB + (size_t)(t + 2) * kstep;
;             const char* a3 = a2 + kstep; const char* b3 = b2 + kstep;
;             PG8_LDB(B0, 0, 0); PG8_LDB(B1, 0, 1); PG8_SCHED; PG8_LDA(At, 0, 0); PG8_STAGE(PG8_SA(1, 1), a1 + hA, voffA);
;             PG8_WAIT_V(8); PG8_WAIT_L(0); PG8_BAR; PG8_MMA(0, 0, At, B0); PG8_MMA(0, 1, At, B1); PG8_BAR; PG8_SCHED;
;             PG8_LDA(At, 0, 1); PG8_STAGE(PG8_SB(0, 0), b2, voffB); PG8_STAGE(PG8_SB(0, 1), b2 + hB, voffB); PG8_STAGE(PG8_SA(0, 0), a2, voffA);
;             PG8_WAIT_V(8); PG8_WAIT_L(0); PG8_BAR; PG8_MMA(1, 0, At, B0); PG8_MMA(1, 1, At, B1); PG8_BAR; PG8_SCHED;
;             PG8_LDB(B0, 1, 0); PG8_LDB(B1, 1, 1); PG8_SCHED; PG8_LDA(At, 1, 0); PG8_STAGE(PG8_SA(0, 1), a2 + hA, voffA);
;             PG8_WAIT_V(8); PG8_WAIT_L(0); PG8_BAR; PG8_MMA(0, 0, At, B0); PG8_MMA(0, 1, At, B1); PG8_BAR; PG8_SCHED;
;             PG8_LDA(At, 1, 1); PG8_STAGE(PG8_SB(1, 0), b3, voffB); PG8_STAGE(PG8_SB(1, 1), b3 + hB, voffB); PG8_STAGE(PG8_SA(1, 0), a3, voffA);
;             PG8_WAIT_V(8); PG8_WAIT_L(0); PG8_BAR; PG8_MMA(1, 0, At, B0); PG8_MMA(1, 1, At, B1); PG8_BAR; PG8_SCHED;
;         }
	s_setprio 1
	s_waitcnt lgkmcnt(0)
	v_mfma_f32_16x16x32_bf16 v[56:59], v[146:149], v[192:195], v[56:59]
	v_mfma_f32_16x16x32_bf16 v[48:51], v[158:161], v[192:195], v[48:51]
	v_mfma_f32_16x16x32_bf16 v[40:43], v[146:149], v[200:203], v[40:43]
	v_mfma_f32_16x16x32_bf16 v[32:35], v[158:161], v[200:203], v[32:35]
	v_mfma_f32_16x16x32_bf16 v[24:27], v[146:149], v[208:211], v[24:27]
	v_mfma_f32_16x16x32_bf16 v[16:19], v[158:161], v[208:211], v[16:19]
	v_mfma_f32_16x16x32_bf16 v[8:11], v[146:149], v[216:219], v[8:11]
	v_mfma_f32_16x16x32_bf16 v[4:7], v[158:161], v[216:219], v[4:7]
	v_mfma_f32_16x16x32_bf16 v[56:59], v[154:157], v[196:199], v[56:59]
	v_mfma_f32_16x16x32_bf16 v[48:51], v[162:165], v[196:199], v[48:51]
	v_mfma_f32_16x16x32_bf16 v[40:43], v[154:157], v[204:207], v[40:43]
	v_mfma_f32_16x16x32_bf16 v[32:35], v[162:165], v[204:207], v[32:35]
	v_mfma_f32_16x16x32_bf16 v[24:27], v[154:157], v[212:215], v[24:27]
	v_mfma_f32_16x16x32_bf16 v[16:19], v[162:165], v[212:215], v[16:19]
	v_mfma_f32_16x16x32_bf16 v[8:11], v[154:157], v[240:243], v[8:11]
	v_mfma_f32_16x16x32_bf16 v[4:7], v[162:165], v[240:243], v[4:7]
	s_setprio 0
	s_setprio 1
	v_mfma_f32_16x16x32_bf16 v[60:63], v[176:179], v[192:195], v[60:63]
	v_mfma_f32_16x16x32_bf16 v[52:55], v[184:187], v[192:195], v[52:55]
	v_mfma_f32_16x16x32_bf16 v[44:47], v[176:179], v[200:203], v[44:47]
	v_mfma_f32_16x16x32_bf16 v[36:39], v[184:187], v[200:203], v[36:39]
	v_mfma_f32_16x16x32_bf16 v[28:31], v[176:179], v[208:211], v[28:31]
	v_mfma_f32_16x16x32_bf16 v[20:23], v[184:187], v[208:211], v[20:23]
	v_mfma_f32_16x16x32_bf16 v[12:15], v[176:179], v[216:219], v[12:15]
	v_mfma_f32_16x16x32_bf16 v[0:3], v[184:187], v[216:219], v[0:3]
	v_mfma_f32_16x16x32_bf16 v[60:63], v[180:183], v[196:199], v[60:63]
	v_mfma_f32_16x16x32_bf16 v[52:55], v[188:191], v[196:199], v[52:55]
	v_mfma_f32_16x16x32_bf16 v[44:47], v[180:183], v[204:207], v[44:47]
	v_mfma_f32_16x16x32_bf16 v[36:39], v[188:191], v[204:207], v[36:39]
	v_mfma_f32_16x16x32_bf16 v[28:31], v[180:183], v[212:215], v[28:31]
	v_mfma_f32_16x16x32_bf16 v[20:23], v[188:191], v[212:215], v[20:23]
	v_mfma_f32_16x16x32_bf16 v[12:15], v[180:183], v[240:243], v[12:15]
	v_mfma_f32_16x16x32_bf16 v[0:3], v[188:191], v[240:243], v[0:3]
	s_setprio 0
	s_barrier
	v_lshl_add_u64 v[142:143], v[142:143], 0, s[80:81]
	v_lshl_add_u64 v[144:145], v[144:145], 0, s[80:81]
	s_mov_b32 s10, s11
	s_cmp_eq_u32 s10, s58
	s_cbranch_scc1 .Lgu_last
.LBB0_308:
	s_add_i32 s11, s10, 2
	s_cmp_eq_u32 s58, s10
	v_lshl_add_u64 v[146:147], v[142:143], 0, s[92:93]
	s_cselect_b64 vcc, -1, 0
	v_add_u32_e32 v150, s33, v151
	s_add_i32 s10, 0, 0x14000
	v_cndmask_b32_e32 v167, v147, v139, vcc
	v_cndmask_b32_e32 v166, v146, v138, vcc
	ds_read_b128 v[146:149], v150
	ds_read_b128 v[154:157], v150 offset:1024
	ds_read_b128 v[158:161], v150 offset:2048
	ds_read_b128 v[162:165], v150 offset:3072
	v_add_u32_e32 v150, s10, v151
	ds_read_b128 v[176:179], v150
	ds_read_b128 v[180:183], v150 offset:1024
	ds_read_b128 v[184:187], v150 offset:2048
	ds_read_b128 v[188:191], v150 offset:3072
	v_cndmask_b32_e32 v221, v145, v141, vcc
	v_cndmask_b32_e32 v220, v144, v140, vcc
	v_lshl_add_u64 v[226:227], v[142:143], 0, v[134:135]
	s_add_i32 m0, s51, 0xc000
	ds_read_b128 v[192:195], v153
	ds_read_b128 v[196:199], v153 offset:1024
	ds_read_b128 v[200:203], v153 offset:2048
	ds_read_b128 v[204:207], v153 offset:3072
	ds_read_b128 v[208:211], v153 offset:4096
	ds_read_b128 v[212:215], v153 offset:5120
	ds_read_b128 v[216:219], v153 offset:6144
	ds_read_b128 v[240:243], v153 offset:7168
	global_load_lds_dwordx4 v[226:227], off
	v_lshl_add_u64 v[226:227], v[142:143], 0, v[136:137]
	s_add_i32 m0, s51, 0xe000
	s_nop 0
	global_load_lds_dwordx4 v[226:227], off
	s_waitcnt vmcnt(8)
	s_waitcnt lgkmcnt(0)
	s_barrier
	s_setprio 1
	s_waitcnt lgkmcnt(0)
	v_mfma_f32_16x16x32_bf16 v[120:123], v[146:149], v[192:195], v[120:123]
	v_mfma_f32_16x16x32_bf16 v[112:115], v[158:161], v[192:195], v[112:115]
	v_mfma_f32_16x16x32_bf16 v[104:107], v[146:149], v[200:203], v[104:107]
	v_mfma_f32_16x16x32_bf16 v[96:99], v[158:161], v[200:203], v[96:99]
	v_mfma_f32_16x16x32_bf16 v[88:91], v[146:149], v[208:211], v[88:91]
	v_mfma_f32_16x16x32_bf16 v[80:83], v[158:161], v[208:211], v[80:83]
	v_mfma_f32_16x16x32_bf16 v[72:75], v[146:149], v[216:219], v[72:75]
	v_mfma_f32_16x16x32_bf16 v[64:67], v[158:161], v[216:219], v[64:67]
	v_mfma_f32_16x16x32_bf16 v[120:123], v[154:157], v[196:199], v[120:123]
	v_mfma_f32_16x16x32_bf16 v[112:115], v[162:165], v[196:199], v[112:115]
	v_mfma_f32_16x16x32_bf16 v[104:107], v[154:157], v[204:207], v[104:107]
	v_mfma_f32_16x16x32_bf16 v[96:99], v[162:165], v[204:207], v[96:99]
	v_mfma_f32_16x16x32_bf16 v[88:91], v[154:157], v[212:215], v[88:91]
	v_mfma_f32_16x16x32_bf16 v[80:83], v[162:165], v[212:215], v[80:83]
	v_mfma_f32_16x16x32_bf16 v[72:75], v[154:157], v[240:243], v[72:75]
	v_mfma_f32_16x16x32_bf16 v[64:67], v[162:165], v[240:243], v[64:67]
	s_setprio 0
	s_setprio 1
	v_mfma_f32_16x16x32_bf16 v[124:127], v[176:179], v[192:195], v[124:127]
	v_mfma_f32_16x16x32_bf16 v[116:119], v[184:187], v[192:195], v[116:119]
	v_mfma_f32_16x16x32_bf16 v[108:111], v[176:179], v[200:203], v[108:111]
	v_mfma_f32_16x16x32_bf16 v[100:103], v[184:187], v[200:203], v[100:103]
	v_mfma_f32_16x16x32_bf16 v[92:95], v[176:179], v[208:211], v[92:95]
	v_mfma_f32_16x16x32_bf16 v[84:87], v[184:187], v[208:211], v[84:87]
	v_mfma_f32_16x16x32_bf16 v[76:79], v[176:179], v[216:219], v[76:79]
	v_mfma_f32_16x16x32_bf16 v[68:71], v[184:187], v[216:219], v[68:71]
	v_mfma_f32_16x16x32_bf16 v[124:127], v[180:183], v[196:199], v[124:127]
	v_mfma_f32_16x16x32_bf16 v[116:119], v[188:191], v[196:199], v[116:119]
	v_mfma_f32_16x16x32_bf16 v[108:111], v[180:183], v[204:207], v[108:111]
	v_mfma_f32_16x16x32_bf16 v[100:103], v[188:191], v[204:207], v[100:103]
	v_mfma_f32_16x16x32_bf16 v[92:95], v[180:183], v[212:215], v[92:95]
	v_mfma_f32_16x16x32_bf16 v[84:87], v[188:191], v[212:215], v[84:87]
	v_mfma_f32_16x16x32_bf16 v[76:79], v[180:183], v[240:243], v[76:79]
	v_mfma_f32_16x16x32_bf16 v[68:71], v[188:191], v[240:243], v[68:71]
	s_setprio 0
	s_barrier
; #define PG8_STAGE(bufoff, gbase, voff) do { _Pragma("unroll") for (int _i = 0; _i < 2; ++_i) \
;         __builtin_amdgcn_global_load_lds((const unsigned*)((const char*)(gbase) + (voff)[_i]), (LAS unsigned*)(lds + (bufoff) + ldsw + _i * 8192), 16, 0, 0); } while (0)
; #define PG8_LDA(dst, b, h) do { _Pragma("unroll") for (int m = 0; m < 4; ++m) _Pragma("unroll") for (int k = 0; k < 2; ++k) dst[m][k] = *(const LAS bf16x8*)(lds + PG8_SA(b, h) + aoff + m * 2048 + k * 1024); } while (0)
; #define PG8_LDB(dst, b, h) do { _Pragma("unroll") for (int n = 0; n < 2; ++n) _Pragma("unroll") for (int k = 0; k < 2; ++k) dst[n][k] = *(const LAS bf16x8*)(lds + PG8_SB(b, h) + boff + n * 2048 + k * 1024); } while (0)
; #define PG8_MMA(ai, bj, At, Bt) do { __builtin_amdgcn_s_setprio(1); _Pragma("unroll") for (int k = 0; k < 2; ++k) _Pragma("unroll") for (int m = 0; m < 4; ++m) _Pragma("unroll") for (int n = 0; n < 2; ++n) \
;         acc[ai][bj][m][n] = __builtin_amdgcn_mfma_f32_16x16x32_bf16(Bt[n][k], At[m][k], acc[ai][bj][m][n], 0, 0, 0); __builtin_amdgcn_s_setprio(0); } while (0)
; #define PG8_WAIT_V(n) asm volatile("s_waitcnt vmcnt(" #n ")" ::: "memory")
; #define PG8_WAIT_L(n) asm volatile("s_waitcnt lgkmcnt(" #n ")" ::: "memory")
; #define PG8_BAR __builtin_amdgcn_s_barrier()
; #define PG8_SCHED __builtin_amdgcn_sched_barrier(0)
; template <class Epi, bool ALIGN_EPI>
; __device__ __forceinline__ void gemm_phase(LAS unsigned char* lds, const Gemm g, const StaticOrder& S, const Epi& E, const int tid) {
;     ...
;             PG8_LDA(At, 0, 1); PG8_STAGE(PG8_SB(0, 0), b2, voffB); PG8_STAGE(PG8_SB(0, 1), b2 + hB, voffB); PG8_STAGE(PG8_SA(0, 0), a2, voffA);
;             PG8_WAIT_V(8); PG8_WAIT_L(0); PG8_BAR; PG8_MMA(1, 0, At, B0); PG8_MMA(1, 1, At, B1); PG8_BAR; PG8_SCHED;
;             PG8_LDB(B0, 1, 0); PG8_LDB(B1, 1, 1); PG8_SCHED; PG8_LDA(At, 1, 0); PG8_STAGE(PG8_SA(0, 1), a2 + hA, voffA);
;             PG8_WAIT_V(8); PG8_WAIT_L(0); PG8_BAR; PG8_MMA(0, 0, At, B0); PG8_MMA(0, 1, At, B1); PG8_BAR; PG8_SCHED;
;             PG8_LDA(At, 1, 1); PG8_STAGE(PG8_SB(1, 0), b3, voffB); PG8_STAGE(PG8_SB(1, 1), b3 + hB, voffB); PG8_STAGE(PG8_SA(1, 0), a3, voffA);
	s_add_i32 s65, s33, s45
	v_lshl_add_u64 v[226:227], v[220:221], 0, v[168:169]
	s_mov_b32 m0, s65
	ds_read_b128 v[192:195], v153 offset:16384
	ds_read_b128 v[196:199], v153 offset:17408
	ds_read_b128 v[200:203], v153 offset:18432
	ds_read_b128 v[204:207], v153 offset:19456
	ds_read_b128 v[208:211], v153 offset:20480
	ds_read_b128 v[212:215], v153 offset:21504
	ds_read_b128 v[216:219], v153 offset:22528
	ds_read_b128 v[240:243], v153 offset:23552
	global_load_lds_dwordx4 v[226:227], off
	v_lshl_add_u64 v[244:245], v[220:221], 0, v[128:129]
	s_add_i32 m0, s65, 0x2000
	v_lshl_add_u64 v[220:221], v[220:221], 0, s[12:13]
	s_add_i32 s10, s10, s45
	global_load_lds_dwordx4 v[244:245], off
	v_lshl_add_u64 v[246:247], v[220:221], 0, v[168:169]
	s_mov_b32 m0, s10
	v_lshl_add_u64 v[220:221], v[220:221], 0, v[128:129]
	global_load_lds_dwordx4 v[246:247], off
	s_add_i32 m0, s10, 0x2000
	v_lshl_add_u64 v[248:249], v[166:167], 0, v[132:133]
	global_load_lds_dwordx4 v[220:221], off
	s_mov_b32 m0, s51
	v_lshl_add_u64 v[250:251], v[166:167], 0, v[130:131]
	global_load_lds_dwordx4 v[248:249], off
	s_mov_b32 m0, s52
	s_nop 0
	global_load_lds_dwordx4 v[250:251], off
	s_waitcnt vmcnt(8)
	s_waitcnt lgkmcnt(0)
	s_barrier
	s_setprio 1
	s_waitcnt lgkmcnt(0)
	v_mfma_f32_16x16x32_bf16 v[56:59], v[146:149], v[192:195], v[56:59]
	v_mfma_f32_16x16x32_bf16 v[48:51], v[158:161], v[192:195], v[48:51]
	v_mfma_f32_16x16x32_bf16 v[40:43], v[146:149], v[200:203], v[40:43]
	v_mfma_f32_16x16x32_bf16 v[32:35], v[158:161], v[200:203], v[32:35]
	v_mfma_f32_16x16x32_bf16 v[24:27], v[146:149], v[208:211], v[24:27]
	v_mfma_f32_16x16x32_bf16 v[16:19], v[158:161], v[208:211], v[16:19]
	v_mfma_f32_16x16x32_bf16 v[8:11], v[146:149], v[216:219], v[8:11]
	v_mfma_f32_16x16x32_bf16 v[4:7], v[158:161], v[216:219], v[4:7]
	v_mfma_f32_16x16x32_bf16 v[56:59], v[154:157], v[196:199], v[56:59]
	v_mfma_f32_16x16x32_bf16 v[48:51], v[162:165], v[196:199], v[48:51]
	v_mfma_f32_16x16x32_bf16 v[40:43], v[154:157], v[204:207], v[40:43]
	v_mfma_f32_16x16x32_bf16 v[32:35], v[162:165], v[204:207], v[32:35]
	v_mfma_f32_16x16x32_bf16 v[24:27], v[154:157], v[212:215], v[24:27]
	v_mfma_f32_16x16x32_bf16 v[16:19], v[162:165], v[212:215], v[16:19]
	v_mfma_f32_16x16x32_bf16 v[8:11], v[154:157], v[240:243], v[8:11]
	v_mfma_f32_16x16x32_bf16 v[4:7], v[162:165], v[240:243], v[4:7]
	s_setprio 0
	s_setprio 1
	v_mfma_f32_16x16x32_bf16 v[60:63], v[176:179], v[192:195], v[60:63]
	v_mfma_f32_16x16x32_bf16 v[52:55], v[184:187], v[192:195], v[52:55]
	v_mfma_f32_16x16x32_bf16 v[44:47], v[176:179], v[200:203], v[44:47]
	v_mfma_f32_16x16x32_bf16 v[36:39], v[184:187], v[200:203], v[36:39]
	v_mfma_f32_16x16x32_bf16 v[28:31], v[176:179], v[208:211], v[28:31]
	v_mfma_f32_16x16x32_bf16 v[20:23], v[184:187], v[208:211], v[20:23]
	v_mfma_f32_16x16x32_bf16 v[12:15], v[176:179], v[216:219], v[12:15]
	v_mfma_f32_16x16x32_bf16 v[0:3], v[184:187], v[216:219], v[0:3]
	v_mfma_f32_16x16x32_bf16 v[60:63], v[180:183], v[196:199], v[60:63]
	v_mfma_f32_16x16x32_bf16 v[52:55], v[188:191], v[196:199], v[52:55]
	v_mfma_f32_16x16x32_bf16 v[44:47], v[180:183], v[204:207], v[44:47]
	v_mfma_f32_16x16x32_bf16 v[36:39], v[188:191], v[204:207], v[36:39]
	v_mfma_f32_16x16x32_bf16 v[28:31], v[180:183], v[212:215], v[28:31]
	v_mfma_f32_16x16x32_bf16 v[20:23], v[188:191], v[212:215], v[20:23]
	v_mfma_f32_16x16x32_bf16 v[12:15], v[180:183], v[240:243], v[12:15]
	v_mfma_f32_16x16x32_bf16 v[0:3], v[188:191], v[240:243], v[0:3]
	s_setprio 0
	s_barrier
	s_add_i32 s10, 0, 0x18000
	v_add_u32_e32 v150, s10, v151
	s_add_i32 s65, 0, 0x1c000
	ds_read_b128 v[146:149], v150
	ds_read_b128 v[154:157], v150 offset:1024
	ds_read_b128 v[158:161], v150 offset:2048
	ds_read_b128 v[162:165], v150 offset:3072
	v_add_u32_e32 v150, s65, v151
	ds_read_b128 v[176:179], v150
	ds_read_b128 v[180:183], v150 offset:1024
	ds_read_b128 v[184:187], v150 offset:2048
	ds_read_b128 v[188:191], v150 offset:3072
	v_lshl_add_u64 v[166:167], v[166:167], 0, s[94:95]
	s_mov_b32 m0, s53
	v_lshl_add_u64 v[252:253], v[166:167], 0, v[132:133]
	ds_read_b128 v[192:195], v153 offset:32768
	ds_read_b128 v[196:199], v153 offset:33792
	ds_read_b128 v[200:203], v153 offset:34816
	ds_read_b128 v[204:207], v153 offset:35840
	ds_read_b128 v[208:211], v153 offset:36864
	ds_read_b128 v[212:215], v153 offset:37888
	ds_read_b128 v[216:219], v153 offset:38912
	ds_read_b128 v[240:243], v153 offset:39936
	global_load_lds_dwordx4 v[252:253], off
	v_lshl_add_u64 v[166:167], v[166:167], 0, v[130:131]
	s_mov_b32 m0, s54
	s_nop 0
	global_load_lds_dwordx4 v[166:167], off
	s_waitcnt vmcnt(8)
	s_waitcnt lgkmcnt(0)
	s_barrier
; #define PG8_STAGE(bufoff, gbase, voff) do { _Pragma("unroll") for (int _i = 0; _i < 2; ++_i) \
;         __builtin_amdgcn_global_load_lds((const unsigned*)((const char*)(gbase) + (voff)[_i]), (LAS unsigned*)(lds + (bufoff) + ldsw + _i * 8192), 16, 0, 0); } while (0)
; #define PG8_LDA(dst, b, h) do { _Pragma("unroll") for (int m = 0; m < 4; ++m) _Pragma("unroll") for (int k = 0; k < 2; ++k) dst[m][k] = *(const LAS bf16x8*)(lds + PG8_SA(b, h) + aoff + m * 2048 + k * 1024); } while (0)
; #define PG8_MMA(ai, bj, At, Bt) do { __builtin_amdgcn_s_setprio(1); _Pragma("unroll") for (int k = 0; k < 2; ++k) _Pragma("unroll") for (int m = 0; m < 4; ++m) _Pragma("unroll") for (int n = 0; n < 2; ++n) \
;         acc[ai][bj][m][n] = __builtin_amdgcn_mfma_f32_16x16x32_bf16(Bt[n][k], At[m][k], acc[ai][bj][m][n], 0, 0, 0); __builtin_amdgcn_s_setprio(0); } while (0)
; #define PG8_WAIT_V(n) asm volatile("s_waitcnt vmcnt(" #n ")" ::: "memory")
; #define PG8_WAIT_L(n) asm volatile("s_waitcnt lgkmcnt(" #n ")" ::: "memory")
; #define PG8_BAR __builtin_amdgcn_s_barrier()
; #define PG8_SCHED __builtin_amdgcn_sched_barrier(0)
; template <class Epi, bool ALIGN_EPI>
; __device__ __forceinline__ void gemm_phase(LAS unsigned char* lds, const Gemm g, const StaticOrder& S, const Epi& E, const int tid) {
;     ...
;             PG8_WAIT_V(8); PG8_WAIT_L(0); PG8_BAR; PG8_MMA(0, 0, At, B0); PG8_MMA(0, 1, At, B1); PG8_BAR; PG8_SCHED;
;             PG8_LDA(At, 1, 1); PG8_STAGE(PG8_SB(1, 0), b3, voffB); PG8_STAGE(PG8_SB(1, 1), b3 + hB, voffB); PG8_STAGE(PG8_SA(1, 0), a3, voffA);
;             PG8_WAIT_V(8); PG8_WAIT_L(0); PG8_BAR; PG8_MMA(1, 0, At, B0); PG8_MMA(1, 1, At, B1); PG8_BAR; PG8_SCHED;
;         }
	s_setprio 1
	s_waitcnt lgkmcnt(0)
	v_mfma_f32_16x16x32_bf16 v[120:123], v[146:149], v[192:195], v[120:123]
	v_mfma_f32_16x16x32_bf16 v[112:115], v[158:161], v[192:195], v[112:115]
	v_mfma_f32_16x16x32_bf16 v[104:107], v[146:149], v[200:203], v[104:107]
	v_mfma_f32_16x16x32_bf16 v[96:99], v[158:161], v[200:203], v[96:99]
	v_mfma_f32_16x16x32_bf16 v[88:91], v[146:149], v[208:211], v[88:91]
	v_mfma_f32_16x16x32_bf16 v[80:83], v[158:161], v[208:211], v[80:83]
	v_mfma_f32_16x16x32_bf16 v[72:75], v[146:149], v[216:219], v[72:75]
	v_mfma_f32_16x16x32_bf16 v[64:67], v[158:161], v[216:219], v[64:67]
	v_mfma_f32_16x16x32_bf16 v[120:123], v[154:157], v[196:199], v[120:123]
	v_mfma_f32_16x16x32_bf16 v[112:115], v[162:165], v[196:199], v[112:115]
	v_mfma_f32_16x16x32_bf16 v[104:107], v[154:157], v[204:207], v[104:107]
	v_mfma_f32_16x16x32_bf16 v[96:99], v[162:165], v[204:207], v[96:99]
	v_mfma_f32_16x16x32_bf16 v[88:91], v[154:157], v[212:215], v[88:91]
	v_mfma_f32_16x16x32_bf16 v[80:83], v[162:165], v[212:215], v[80:83]
	v_mfma_f32_16x16x32_bf16 v[72:75], v[154:157], v[240:243], v[72:75]
	v_mfma_f32_16x16x32_bf16 v[64:67], v[162:165], v[240:243], v[64:67]
	s_setprio 0
	s_setprio 1
	v_mfma_f32_16x16x32_bf16 v[124:127], v[176:179], v[192:195], v[124:127]
	v_mfma_f32_16x16x32_bf16 v[116:119], v[184:187], v[192:195], v[116:119]
	v_mfma_f32_16x16x32_bf16 v[108:111], v[176:179], v[200:203], v[108:111]
	v_mfma_f32_16x16x32_bf16 v[100:103], v[184:187], v[200:203], v[100:103]
	v_mfma_f32_16x16x32_bf16 v[92:95], v[176:179], v[208:211], v[92:95]
	v_mfma_f32_16x16x32_bf16 v[84:87], v[184:187], v[208:211], v[84:87]
	v_mfma_f32_16x16x32_bf16 v[76:79], v[176:179], v[216:219], v[76:79]
	v_mfma_f32_16x16x32_bf16 v[68:71], v[184:187], v[216:219], v[68:71]
	v_mfma_f32_16x16x32_bf16 v[124:127], v[180:183], v[196:199], v[124:127]
	v_mfma_f32_16x16x32_bf16 v[116:119], v[188:191], v[196:199], v[116:119]
	v_mfma_f32_16x16x32_bf16 v[108:111], v[180:183], v[204:207], v[108:111]
	v_mfma_f32_16x16x32_bf16 v[100:103], v[188:191], v[204:207], v[100:103]
	v_mfma_f32_16x16x32_bf16 v[92:95], v[180:183], v[212:215], v[92:95]
	v_mfma_f32_16x16x32_bf16 v[84:87], v[188:191], v[212:215], v[84:87]
	v_mfma_f32_16x16x32_bf16 v[76:79], v[180:183], v[240:243], v[76:79]
	v_mfma_f32_16x16x32_bf16 v[68:71], v[188:191], v[240:243], v[68:71]
	s_setprio 0
	s_barrier
	s_add_i32 s10, s10, s45
	v_lshl_add_u64 v[166:167], v[226:227], 0, s[92:93]
	s_mov_b32 m0, s10
	ds_read_b128 v[192:195], v153 offset:49152
	ds_read_b128 v[196:199], v153 offset:50176
	ds_read_b128 v[200:203], v153 offset:51200
	ds_read_b128 v[204:207], v153 offset:52224
	ds_read_b128 v[208:211], v153 offset:53248
	ds_read_b128 v[212:215], v153 offset:54272
	ds_read_b128 v[216:219], v153 offset:55296
	ds_read_b128 v[240:243], v153 offset:56320
	global_load_lds_dwordx4 v[166:167], off
	v_lshl_add_u64 v[166:167], v[244:245], 0, s[92:93]
	s_add_i32 m0, s10, 0x2000
	s_add_i32 s10, s65, s45
	global_load_lds_dwordx4 v[166:167], off
	v_lshl_add_u64 v[166:167], v[246:247], 0, s[92:93]
	s_mov_b32 m0, s10
	s_nop 0
	global_load_lds_dwordx4 v[166:167], off
	v_lshl_add_u64 v[166:167], v[220:221], 0, s[92:93]
	s_add_i32 m0, s10, 0x2000
	s_nop 0
	global_load_lds_dwordx4 v[166:167], off
	v_lshl_add_u64 v[166:167], v[248:249], 0, s[92:93]
	s_mov_b32 m0, s56
	s_nop 0
	global_load_lds_dwordx4 v[166:167], off
	v_lshl_add_u64 v[166:167], v[250:251], 0, s[92:93]
	s_mov_b32 m0, s57
	s_nop 0
	global_load_lds_dwordx4 v[166:167], off
	s_waitcnt vmcnt(8)
	s_waitcnt lgkmcnt(0)
	s_barrier
	s_setprio 1
	s_waitcnt lgkmcnt(0)
	v_mfma_f32_16x16x32_bf16 v[56:59], v[146:149], v[192:195], v[56:59]
	v_mfma_f32_16x16x32_bf16 v[48:51], v[158:161], v[192:195], v[48:51]
	v_mfma_f32_16x16x32_bf16 v[40:43], v[146:149], v[200:203], v[40:43]
	v_mfma_f32_16x16x32_bf16 v[32:35], v[158:161], v[200:203], v[32:35]
	v_mfma_f32_16x16x32_bf16 v[24:27], v[146:149], v[208:211], v[24:27]
	v_mfma_f32_16x16x32_bf16 v[16:19], v[158:161], v[208:211], v[16:19]
	v_mfma_f32_16x16x32_bf16 v[8:11], v[146:149], v[216:219], v[8:11]
	v_mfma_f32_16x16x32_bf16 v[4:7], v[158:161], v[216:219], v[4:7]
	v_mfma_f32_16x16x32_bf16 v[56:59], v[154:157], v[196:199], v[56:59]
	v_mfma_f32_16x16x32_bf16 v[48:51], v[162:165], v[196:199], v[48:51]
	v_mfma_f32_16x16x32_bf16 v[40:43], v[154:157], v[204:207], v[40:43]
	v_mfma_f32_16x16x32_bf16 v[32:35], v[162:165], v[204:207], v[32:35]
	v_mfma_f32_16x16x32_bf16 v[24:27], v[154:157], v[212:215], v[24:27]
	v_mfma_f32_16x16x32_bf16 v[16:19], v[162:165], v[212:215], v[16:19]
	v_mfma_f32_16x16x32_bf16 v[8:11], v[154:157], v[240:243], v[8:11]
	v_mfma_f32_16x16x32_bf16 v[4:7], v[162:165], v[240:243], v[4:7]
	s_setprio 0
	s_setprio 1
	v_mfma_f32_16x16x32_bf16 v[60:63], v[176:179], v[192:195], v[60:63]
	v_mfma_f32_16x16x32_bf16 v[52:55], v[184:187], v[192:195], v[52:55]
	v_mfma_f32_16x16x32_bf16 v[44:47], v[176:179], v[200:203], v[44:47]
	v_mfma_f32_16x16x32_bf16 v[36:39], v[184:187], v[200:203], v[36:39]
	v_mfma_f32_16x16x32_bf16 v[28:31], v[176:179], v[208:211], v[28:31]
	v_mfma_f32_16x16x32_bf16 v[20:23], v[184:187], v[208:211], v[20:23]
	v_mfma_f32_16x16x32_bf16 v[12:15], v[176:179], v[216:219], v[12:15]
	v_mfma_f32_16x16x32_bf16 v[0:3], v[184:187], v[216:219], v[0:3]
	v_mfma_f32_16x16x32_bf16 v[60:63], v[180:183], v[196:199], v[60:63]
	v_mfma_f32_16x16x32_bf16 v[52:55], v[188:191], v[196:199], v[52:55]
	v_mfma_f32_16x16x32_bf16 v[44:47], v[180:183], v[204:207], v[44:47]
	v_mfma_f32_16x16x32_bf16 v[36:39], v[188:191], v[204:207], v[36:39]
	v_mfma_f32_16x16x32_bf16 v[28:31], v[180:183], v[212:215], v[28:31]
	v_mfma_f32_16x16x32_bf16 v[20:23], v[188:191], v[212:215], v[20:23]
	v_mfma_f32_16x16x32_bf16 v[12:15], v[180:183], v[240:243], v[12:15]
	v_mfma_f32_16x16x32_bf16 v[0:3], v[188:191], v[240:243], v[0:3]
	s_setprio 0
	s_barrier
	v_lshl_add_u64 v[142:143], v[142:143], 0, s[80:81]
	v_lshl_add_u64 v[144:145], v[144:145], 0, s[80:81]
	s_mov_b32 s10, s11
	s_cmp_lg_u32 s10, s58
	s_cbranch_scc1 .LBB0_308
; #define PG8_STAGE(bufoff, gbase, voff) do { _Pragma("unroll") for (int _i = 0; _i < 2; ++_i) \
;         __builtin_amdgcn_global_load_lds((const unsigned*)((const char*)(gbase) + (voff)[_i]), (LAS unsigned*)(lds + (bufoff) + ldsw + _i * 8192), 16, 0, 0); } while (0)
; #define PG8_LDA(dst, b, h) do { _Pragma("unroll") for (int m = 0; m < 4; ++m) _Pragma("unroll") for (int k = 0; k < 2; ++k) dst[m][k] = *(const LAS bf16x8*)(lds + PG8_SA(b, h) + aoff + m * 2048 + k * 1024); } while (0)
; #define PG8_LDB(dst, b, h) do { _Pragma("unroll") for (int n = 0; n < 2; ++n) _Pragma("unroll") for (int k = 0; k < 2; ++k) dst[n][k] = *(const LAS bf16x8*)(lds + PG8_SB(b, h) + boff + n * 2048 + k * 1024); } while (0)
; #define PG8_MMA(ai, bj, At, Bt) do { __builtin_amdgcn_s_setprio(1); _Pragma("unroll") for (int k = 0; k < 2; ++k) _Pragma("unroll") for (int m = 0; m < 4; ++m) _Pragma("unroll") for (int n = 0; n < 2; ++n) \
;         acc[ai][bj][m][n] = __builtin_amdgcn_mfma_f32_16x16x32_bf16(Bt[n][k], At[m][k], acc[ai][bj][m][n], 0, 0, 0); __builtin_amdgcn_s_setprio(0); } while (0)
; #define PG8_WAIT_V(n) asm volatile("s_waitcnt vmcnt(" #n ")" ::: "memory")
; #define PG8_WAIT_L(n) asm volatile("s_waitcnt lgkmcnt(" #n ")" ::: "memory")
; #define PG8_BAR __builtin_amdgcn_s_barrier()
; #define PG8_SCHED __builtin_amdgcn_sched_barrier(0)
; template <class Epi, bool ALIGN_EPI>
; __device__ __forceinline__ void gemm_phase(LAS unsigned char* lds, const Gemm g, const StaticOrder& S, const Epi& E, const int tid) {
;     ...
;         for (int t = 0; t < nt; t += 2) {
;             const bool last = (t == nt - 2);
;             const char* a1 = cA + (size_t)(t + 1) * kstep;
;             const char* a2 = last ? nA : cA + (size_t)(t + 2) * kstep; const char* b2 = last ? nB : cB + (size_t)(t + 2) * kstep;
;             const char* a3 = a2 + kstep; const char* b3 = b2 + kstep;
;             PG8_LDB(B0, 0, 0); PG8_LDB(B1, 0, 1); PG8_SCHED; PG8_LDA(At, 0, 0); PG8_STAGE(PG8_SA(1, 1), a1 + hA, voffA);
;             PG8_WAIT_V(8); PG8_WAIT_L(0); PG8_BAR; PG8_MMA(0, 0, At, B0); PG8_MMA(0, 1, At, B1); PG8_BAR; PG8_SCHED;
;             PG8_LDA(At, 0, 1); PG8_STAGE(PG8_SB(0, 0), b2, voffB); PG8_STAGE(PG8_SB(0, 1), b2 + hB, voffB); PG8_STAGE(PG8_SA(0, 0), a2, voffA);
;             PG8_WAIT_V(8); PG8_WAIT_L(0); PG8_BAR; PG8_MMA(1, 0, At, B0); PG8_MMA(1, 1, At, B1); PG8_BAR; PG8_SCHED;
.Lgu_last:
	s_add_i32 s11, s10, 2
	s_cmp_eq_u32 s58, s10
	v_lshl_add_u64 v[146:147], v[142:143], 0, s[92:93]
	s_cselect_b64 vcc, -1, 0
	v_add_u32_e32 v150, s33, v151
	s_add_i32 s10, 0, 0x14000
	v_cndmask_b32_e32 v167, v147, v139, vcc
	v_cndmask_b32_e32 v166, v146, v138, vcc
	ds_read_b128 v[146:149], v150
	ds_read_b128 v[154:157], v150 offset:1024
	ds_read_b128 v[158:161], v150 offset:2048
	ds_read_b128 v[162:165], v150 offset:3072
	v_add_u32_e32 v150, s10, v151
	ds_read_b128 v[176:179], v150
	ds_read_b128 v[180:183], v150 offset:1024
	ds_read_b128 v[184:187], v150 offset:2048
	ds_read_b128 v[188:191], v150 offset:3072
	v_cndmask_b32_e32 v221, v145, v141, vcc
	v_cndmask_b32_e32 v220, v144, v140, vcc
	v_lshl_add_u64 v[226:227], v[142:143], 0, v[134:135]
	s_add_i32 m0, s51, 0xc000
	ds_read_b128 v[192:195], v153
	ds_read_b128 v[196:199], v153 offset:1024
	ds_read_b128 v[200:203], v153 offset:2048
	ds_read_b128 v[204:207], v153 offset:3072
	ds_read_b128 v[208:211], v153 offset:4096
	ds_read_b128 v[212:215], v153 offset:5120
	ds_read_b128 v[216:219], v153 offset:6144
	ds_read_b128 v[240:243], v153 offset:7168
	global_load_lds_dwordx4 v[226:227], off
	v_lshl_add_u64 v[226:227], v[142:143], 0, v[136:137]
	s_add_i32 m0, s51, 0xe000
	s_nop 0
	global_load_lds_dwordx4 v[226:227], off
	s_waitcnt vmcnt(8)
	s_waitcnt lgkmcnt(0)
	s_barrier
	s_setprio 1
	s_waitcnt lgkmcnt(0)
	v_mfma_f32_16x16x32_bf16 v[120:123], v[146:149], v[192:195], v[120:123]
	v_mfma_f32_16x16x32_bf16 v[112:115], v[158:161], v[192:195], v[112:115]
	v_mfma_f32_16x16x32_bf16 v[104:107], v[146:149], v[200:203], v[104:107]
	v_mfma_f32_16x16x32_bf16 v[96:99], v[158:161], v[200:203], v[96:99]
	v_mfma_f32_16x16x32_bf16 v[88:91], v[146:149], v[208:211], v[88:91]
	v_mfma_f32_16x16x32_bf16 v[80:83], v[158:161], v[208:211], v[80:83]
	v_mfma_f32_16x16x32_bf16 v[72:75], v[146:149], v[216:219], v[72:75]
	v_mfma_f32_16x16x32_bf16 v[64:67], v[158:161], v[216:219], v[64:67]
	v_mfma_f32_16x16x32_bf16 v[120:123], v[154:157], v[196:199], v[120:123]
	v_mfma_f32_16x16x32_bf16 v[112:115], v[162:165], v[196:199], v[112:115]
	v_mfma_f32_16x16x32_bf16 v[104:107], v[154:157], v[204:207], v[104:107]
	v_mfma_f32_16x16x32_bf16 v[96:99], v[162:165], v[204:207], v[96:99]
	v_mfma_f32_16x16x32_bf16 v[88:91], v[154:157], v[212:215], v[88:91]
	v_mfma_f32_16x16x32_bf16 v[80:83], v[162:165], v[212:215], v[80:83]
	v_mfma_f32_16x16x32_bf16 v[72:75], v[154:157], v[240:243], v[72:75]
	v_mfma_f32_16x16x32_bf16 v[64:67], v[162:165], v[240:243], v[64:67]
	s_setprio 0
	s_setprio 1
	v_mfma_f32_16x16x32_bf16 v[124:127], v[176:179], v[192:195], v[124:127]
	v_mfma_f32_16x16x32_bf16 v[116:119], v[184:187], v[192:195], v[116:119]
	v_mfma_f32_16x16x32_bf16 v[108:111], v[176:179], v[200:203], v[108:111]
	v_mfma_f32_16x16x32_bf16 v[100:103], v[184:187], v[200:203], v[100:103]
	v_mfma_f32_16x16x32_bf16 v[92:95], v[176:179], v[208:211], v[92:95]
	v_mfma_f32_16x16x32_bf16 v[84:87], v[184:187], v[208:211], v[84:87]
	v_mfma_f32_16x16x32_bf16 v[76:79], v[176:179], v[216:219], v[76:79]
	v_mfma_f32_16x16x32_bf16 v[68:71], v[184:187], v[216:219], v[68:71]
	v_mfma_f32_16x16x32_bf16 v[124:127], v[180:183], v[196:199], v[124:127]
	v_mfma_f32_16x16x32_bf16 v[116:119], v[188:191], v[196:199], v[116:119]
	v_mfma_f32_16x16x32_bf16 v[108:111], v[180:183], v[204:207], v[108:111]
	v_mfma_f32_16x16x32_bf16 v[100:103], v[188:191], v[204:207], v[100:103]
	v_mfma_f32_16x16x32_bf16 v[92:95], v[180:183], v[212:215], v[92:95]
	v_mfma_f32_16x16x32_bf16 v[84:87], v[188:191], v[212:215], v[84:87]
	v_mfma_f32_16x16x32_bf16 v[76:79], v[180:183], v[240:243], v[76:79]
	v_mfma_f32_16x16x32_bf16 v[68:71], v[188:191], v[240:243], v[68:71]
	s_setprio 0
	s_barrier
	s_add_i32 s65, s33, s45
	v_lshl_add_u64 v[226:227], v[220:221], 0, v[168:169]
	s_mov_b32 m0, s65
	ds_read_b128 v[192:195], v153 offset:16384
	ds_read_b128 v[196:199], v153 offset:17408
	ds_read_b128 v[200:203], v153 offset:18432
	ds_read_b128 v[204:207], v153 offset:19456
	ds_read_b128 v[208:211], v153 offset:20480
	ds_read_b128 v[212:215], v153 offset:21504
	ds_read_b128 v[216:219], v153 offset:22528
	ds_read_b128 v[240:243], v153 offset:23552
	global_load_lds_dwordx4 v[226:227], off
	v_lshl_add_u64 v[244:245], v[220:221], 0, v[128:129]
	s_add_i32 m0, s65, 0x2000
	v_lshl_add_u64 v[220:221], v[220:221], 0, s[12:13]
	s_add_i32 s10, s10, s45
	global_load_lds_dwordx4 v[244:245], off
	v_lshl_add_u64 v[246:247], v[220:221], 0, v[168:169]
	s_mov_b32 m0, s10
	v_lshl_add_u64 v[220:221], v[220:221], 0, v[128:129]
	global_load_lds_dwordx4 v[246:247], off
	s_add_i32 m0, s10, 0x2000
	v_lshl_add_u64 v[248:249], v[166:167], 0, v[132:133]
	global_load_lds_dwordx4 v[220:221], off
	s_mov_b32 m0, s51
	v_lshl_add_u64 v[250:251], v[166:167], 0, v[130:131]
	global_load_lds_dwordx4 v[248:249], off
	s_mov_b32 m0, s52
	s_nop 0
	global_load_lds_dwordx4 v[250:251], off
	s_waitcnt vmcnt(8)
	s_waitcnt lgkmcnt(0)
	s_barrier
; #define PG8_STAGE(bufoff, gbase, voff) do { _Pragma("unroll") for (int _i = 0; _i < 2; ++_i) \
;         __builtin_amdgcn_global_load_lds((const unsigned*)((const char*)(gbase) + (voff)[_i]), (LAS unsigned*)(lds + (bufoff) + ldsw + _i * 8192), 16, 0, 0); } while (0)
; #define PG8_LDA(dst, b, h) do { _Pragma("unroll") for (int m = 0; m < 4; ++m) _Pragma("unroll") for (int k = 0; k < 2; ++k) dst[m][k] = *(const LAS bf16x8*)(lds + PG8_SA(b, h) + aoff + m * 2048 + k * 1024); } while (0)
; #define PG8_LDB(dst, b, h) do { _Pragma("unroll") for (int n = 0; n < 2; ++n) _Pragma("unroll") for (int k = 0; k < 2; ++k) dst[n][k] = *(const LAS bf16x8*)(lds + PG8_SB(b, h) + boff + n * 2048 + k * 1024); } while (0)
; #define PG8_MMA(ai, bj, At, Bt) do { __builtin_amdgcn_s_setprio(1); _Pragma("unroll") for (int k = 0; k < 2; ++k) _Pragma("unroll") for (int m = 0; m < 4; ++m) _Pragma("unroll") for (int n = 0; n < 2; ++n) \
;         acc[ai][bj][m][n] = __builtin_amdgcn_mfma_f32_16x16x32_bf16(Bt[n][k], At[m][k], acc[ai][bj][m][n], 0, 0, 0); __builtin_amdgcn_s_setprio(0); } while (0)
; #define PG8_WAIT_V(n) asm volatile("s_waitcnt vmcnt(" #n ")" ::: "memory")
; #define PG8_WAIT_L(n) asm volatile("s_waitcnt lgkmcnt(" #n ")" ::: "memory")
; #define PG8_BAR __builtin_amdgcn_s_barrier()
; #define PG8_SCHED __builtin_amdgcn_sched_barrier(0)
; template <class Epi, bool ALIGN_EPI>
; __device__ __forceinline__ void gemm_phase(LAS unsigned char* lds, const Gemm g, const StaticOrder& S, const Epi& E, const int tid) {
;     ...
;             PG8_WAIT_V(8); PG8_WAIT_L(0); PG8_BAR; PG8_MMA(1, 0, At, B0); PG8_MMA(1, 1, At, B1); PG8_BAR; PG8_SCHED;
;             PG8_LDB(B0, 1, 0); PG8_LDB(B1, 1, 1); PG8_SCHED; PG8_LDA(At, 1, 0); PG8_STAGE(PG8_SA(0, 1), a2 + hA, voffA);
;             PG8_WAIT_V(8); PG8_WAIT_L(0); PG8_BAR; PG8_MMA(0, 0, At, B0); PG8_MMA(0, 1, At, B1); PG8_BAR; PG8_SCHED;
;             PG8_LDA(At, 1, 1); PG8_STAGE(PG8_SB(1, 0), b3, voffB); PG8_STAGE(PG8_SB(1, 1), b3 + hB, voffB); PG8_STAGE(PG8_SA(1, 0), a3, voffA);
	s_setprio 1
	s_waitcnt lgkmcnt(0)
	v_mfma_f32_16x16x32_bf16 v[56:59], v[146:149], v[192:195], v[56:59]
	v_mfma_f32_16x16x32_bf16 v[48:51], v[158:161], v[192:195], v[48:51]
	v_mfma_f32_16x16x32_bf16 v[40:43], v[146:149], v[200:203], v[40:43]
	v_mfma_f32_16x16x32_bf16 v[32:35], v[158:161], v[200:203], v[32:35]
	v_mfma_f32_16x16x32_bf16 v[24:27], v[146:149], v[208:211], v[24:27]
	v_mfma_f32_16x16x32_bf16 v[16:19], v[158:161], v[208:211], v[16:19]
	v_mfma_f32_16x16x32_bf16 v[8:11], v[146:149], v[216:219], v[8:11]
	v_mfma_f32_16x16x32_bf16 v[4:7], v[158:161], v[216:219], v[4:7]
	v_mfma_f32_16x16x32_bf16 v[56:59], v[154:157], v[196:199], v[56:59]
	v_mfma_f32_16x16x32_bf16 v[48:51], v[162:165], v[196:199], v[48:51]
	v_mfma_f32_16x16x32_bf16 v[40:43], v[154:157], v[204:207], v[40:43]
	v_mfma_f32_16x16x32_bf16 v[32:35], v[162:165], v[204:207], v[32:35]
	v_mfma_f32_16x16x32_bf16 v[24:27], v[154:157], v[212:215], v[24:27]
	v_mfma_f32_16x16x32_bf16 v[16:19], v[162:165], v[212:215], v[16:19]
	v_mfma_f32_16x16x32_bf16 v[8:11], v[154:157], v[240:243], v[8:11]
	v_mfma_f32_16x16x32_bf16 v[4:7], v[162:165], v[240:243], v[4:7]
	s_setprio 0
	s_setprio 1
	v_mfma_f32_16x16x32_bf16 v[60:63], v[176:179], v[192:195], v[60:63]
	v_mfma_f32_16x16x32_bf16 v[52:55], v[184:187], v[192:195], v[52:55]
	v_mfma_f32_16x16x32_bf16 v[44:47], v[176:179], v[200:203], v[44:47]
	v_mfma_f32_16x16x32_bf16 v[36:39], v[184:187], v[200:203], v[36:39]
	v_mfma_f32_16x16x32_bf16 v[28:31], v[176:179], v[208:211], v[28:31]
	v_mfma_f32_16x16x32_bf16 v[20:23], v[184:187], v[208:211], v[20:23]
	v_mfma_f32_16x16x32_bf16 v[12:15], v[176:179], v[216:219], v[12:15]
	v_mfma_f32_16x16x32_bf16 v[0:3], v[184:187], v[216:219], v[0:3]
	v_mfma_f32_16x16x32_bf16 v[60:63], v[180:183], v[196:199], v[60:63]
	v_mfma_f32_16x16x32_bf16 v[52:55], v[188:191], v[196:199], v[52:55]
	v_mfma_f32_16x16x32_bf16 v[44:47], v[180:183], v[204:207], v[44:47]
	v_mfma_f32_16x16x32_bf16 v[36:39], v[188:191], v[204:207], v[36:39]
	v_mfma_f32_16x16x32_bf16 v[28:31], v[180:183], v[212:215], v[28:31]
	v_mfma_f32_16x16x32_bf16 v[20:23], v[188:191], v[212:215], v[20:23]
	v_mfma_f32_16x16x32_bf16 v[12:15], v[180:183], v[240:243], v[12:15]
	v_mfma_f32_16x16x32_bf16 v[0:3], v[188:191], v[240:243], v[0:3]
	s_setprio 0
	s_barrier
	s_add_i32 s10, 0, 0x18000
	v_add_u32_e32 v150, s10, v151
	s_add_i32 s65, 0, 0x1c000
	ds_read_b128 v[146:149], v150
	ds_read_b128 v[154:157], v150 offset:1024
	ds_read_b128 v[158:161], v150 offset:2048
	ds_read_b128 v[162:165], v150 offset:3072
	v_add_u32_e32 v150, s65, v151
	ds_read_b128 v[176:179], v150
	ds_read_b128 v[180:183], v150 offset:1024
	ds_read_b128 v[184:187], v150 offset:2048
	ds_read_b128 v[188:191], v150 offset:3072
	v_lshl_add_u64 v[166:167], v[166:167], 0, s[94:95]
	s_mov_b32 m0, s53
	v_lshl_add_u64 v[252:253], v[166:167], 0, v[132:133]
	ds_read_b128 v[192:195], v153 offset:32768
	ds_read_b128 v[196:199], v153 offset:33792
	ds_read_b128 v[200:203], v153 offset:34816
	ds_read_b128 v[204:207], v153 offset:35840
	ds_read_b128 v[208:211], v153 offset:36864
	ds_read_b128 v[212:215], v153 offset:37888
	ds_read_b128 v[216:219], v153 offset:38912
	ds_read_b128 v[240:243], v153 offset:39936
	global_load_lds_dwordx4 v[252:253], off
	v_lshl_add_u64 v[166:167], v[166:167], 0, v[130:131]
	s_mov_b32 m0, s54
	s_nop 0
	global_load_lds_dwordx4 v[166:167], off
	s_waitcnt vmcnt(8)
	s_waitcnt lgkmcnt(0)
	s_barrier
	s_setprio 1
	s_waitcnt lgkmcnt(0)
	v_mfma_f32_16x16x32_bf16 v[120:123], v[146:149], v[192:195], v[120:123]
	v_mfma_f32_16x16x32_bf16 v[112:115], v[158:161], v[192:195], v[112:115]
	v_mfma_f32_16x16x32_bf16 v[104:107], v[146:149], v[200:203], v[104:107]
	v_mfma_f32_16x16x32_bf16 v[96:99], v[158:161], v[200:203], v[96:99]
	v_mfma_f32_16x16x32_bf16 v[88:91], v[146:149], v[208:211], v[88:91]
	v_mfma_f32_16x16x32_bf16 v[80:83], v[158:161], v[208:211], v[80:83]
	v_mfma_f32_16x16x32_bf16 v[72:75], v[146:149], v[216:219], v[72:75]
	v_mfma_f32_16x16x32_bf16 v[64:67], v[158:161], v[216:219], v[64:67]
	v_mfma_f32_16x16x32_bf16 v[120:123], v[154:157], v[196:199], v[120:123]
	v_mfma_f32_16x16x32_bf16 v[112:115], v[162:165], v[196:199], v[112:115]
	v_mfma_f32_16x16x32_bf16 v[104:107], v[154:157], v[204:207], v[104:107]
	v_mfma_f32_16x16x32_bf16 v[96:99], v[162:165], v[204:207], v[96:99]
	v_mfma_f32_16x16x32_bf16 v[88:91], v[154:157], v[212:215], v[88:91]
	v_mfma_f32_16x16x32_bf16 v[80:83], v[162:165], v[212:215], v[80:83]
	v_mfma_f32_16x16x32_bf16 v[72:75], v[154:157], v[240:243], v[72:75]
	v_mfma_f32_16x16x32_bf16 v[64:67], v[162:165], v[240:243], v[64:67]
	s_setprio 0
	s_setprio 1
	v_mfma_f32_16x16x32_bf16 v[124:127], v[176:179], v[192:195], v[124:127]
	v_mfma_f32_16x16x32_bf16 v[116:119], v[184:187], v[192:195], v[116:119]
	v_mfma_f32_16x16x32_bf16 v[108:111], v[176:179], v[200:203], v[108:111]
	v_mfma_f32_16x16x32_bf16 v[100:103], v[184:187], v[200:203], v[100:103]
	v_mfma_f32_16x16x32_bf16 v[92:95], v[176:179], v[208:211], v[92:95]
	v_mfma_f32_16x16x32_bf16 v[84:87], v[184:187], v[208:211], v[84:87]
	v_mfma_f32_16x16x32_bf16 v[76:79], v[176:179], v[216:219], v[76:79]
	v_mfma_f32_16x16x32_bf16 v[68:71], v[184:187], v[216:219], v[68:71]
	v_mfma_f32_16x16x32_bf16 v[124:127], v[180:183], v[196:199], v[124:127]
	v_mfma_f32_16x16x32_bf16 v[116:119], v[188:191], v[196:199], v[116:119]
	v_mfma_f32_16x16x32_bf16 v[108:111], v[180:183], v[204:207], v[108:111]
	v_mfma_f32_16x16x32_bf16 v[100:103], v[188:191], v[204:207], v[100:103]
	v_mfma_f32_16x16x32_bf16 v[92:95], v[180:183], v[212:215], v[92:95]
	v_mfma_f32_16x16x32_bf16 v[84:87], v[188:191], v[212:215], v[84:87]
	v_mfma_f32_16x16x32_bf16 v[76:79], v[180:183], v[240:243], v[76:79]
	v_mfma_f32_16x16x32_bf16 v[68:71], v[188:191], v[240:243], v[68:71]
	s_setprio 0
	s_barrier
; __device__ __forceinline__ unsigned cvt_pk_bf16(float lo, float hi) { unsigned r; asm volatile("v_cvt_pk_bf16_f32 %0, %1, %2" : "=v"(r) : "v"(lo), "v"(hi)); return r; }
; __device__ __forceinline__ float siluf_(float x) { return x * sigmoidf_(x); }
; #define PG8_STAGE(bufoff, gbase, voff) do { _Pragma("unroll") for (int _i = 0; _i < 2; ++_i) \
;         __builtin_amdgcn_global_load_lds((const unsigned*)((const char*)(gbase) + (voff)[_i]), (LAS unsigned*)(lds + (bufoff) + ldsw + _i * 8192), 16, 0, 0); } while (0)
; #define PG8_LDA(dst, b, h) do { _Pragma("unroll") for (int m = 0; m < 4; ++m) _Pragma("unroll") for (int k = 0; k < 2; ++k) dst[m][k] = *(const LAS bf16x8*)(lds + PG8_SA(b, h) + aoff + m * 2048 + k * 1024); } while (0)
; #define PG8_WAIT_V(n) asm volatile("s_waitcnt vmcnt(" #n ")" ::: "memory")
; #define PG8_WAIT_L(n) asm volatile("s_waitcnt lgkmcnt(" #n ")" ::: "memory")
; #define PG8_BAR __builtin_amdgcn_s_barrier()
; #define PG8_SCHED __builtin_amdgcn_sched_barrier(0)
;     __device__ __forceinline__ void operator()(const f32x4 (&acc)[2][2][4][2], const Unit& u, int wr, int wc, int fr, int fq) const {
;         const int row0 = u.pm * BM + wr * 64 + fr, col0 = u.pn * HALF + wc * 32 + 8 * fq;
;         float rsv[2][4]; load_rstd(rsv, ssq, row0);
; #pragma unroll
;         for (int ai = 0; ai < 2; ++ai)
; #pragma unroll
;             for (int m = 0; m < 4; ++m) { const int row = row0 + ai * HALF + m * 16; bf16_t* rowp = O + (size_t)row * ldc + col0; const float rs = rsv[ai][m];
;                 f32x4 v0, v1;
; #pragma unroll
;                 for (int j = 0; j < 4; ++j) { v0[j] = siluf_(acc[ai][0][m][0][j] * rs) * (acc[ai][1][m][0][j] * rs); v1[j] = siluf_(acc[ai][0][m][1][j] * rs) * (acc[ai][1][m][1][j] * rs); }
;                 u32x4 w; w.x = cvt_pk_bf16(v0[0], v0[1]); w.y = cvt_pk_bf16(v0[2], v0[3]); w.z = cvt_pk_bf16(v1[0], v1[1]); w.w = cvt_pk_bf16(v1[2], v1[3]);
;                 *(u32x4*)rowp = w; }
; template <class Epi, bool ALIGN_EPI>
; __device__ __forceinline__ void gemm_phase(LAS unsigned char* lds, const Gemm g, const StaticOrder& S, const Epi& E, const int tid) {
;     ...
;             PG8_LDA(At, 1, 1); PG8_STAGE(PG8_SB(1, 0), b3, voffB); PG8_STAGE(PG8_SB(1, 1), b3 + hB, voffB); PG8_STAGE(PG8_SA(1, 0), a3, voffA);
;             PG8_WAIT_V(8); PG8_WAIT_L(0); PG8_BAR; PG8_MMA(1, 0, At, B0); PG8_MMA(1, 1, At, B1); PG8_BAR; PG8_SCHED;
	s_add_i32 s10, s10, s45
	v_lshl_add_u64 v[166:167], v[226:227], 0, s[92:93]
	s_mov_b32 m0, s10
	ds_read_b128 v[192:195], v153 offset:49152
	ds_read_b128 v[196:199], v153 offset:50176
	ds_read_b128 v[200:203], v153 offset:51200
	ds_read_b128 v[204:207], v153 offset:52224
	ds_read_b128 v[208:211], v153 offset:53248
	ds_read_b128 v[212:215], v153 offset:54272
	ds_read_b128 v[216:219], v153 offset:55296
	ds_read_b128 v[240:243], v153 offset:56320
	global_load_lds_dwordx4 v[166:167], off
	v_lshl_add_u64 v[166:167], v[244:245], 0, s[92:93]
	s_add_i32 m0, s10, 0x2000
	s_add_i32 s10, s65, s45
	global_load_lds_dwordx4 v[166:167], off
	v_lshl_add_u64 v[166:167], v[246:247], 0, s[92:93]
	s_mov_b32 m0, s10
	s_nop 0
	global_load_lds_dwordx4 v[166:167], off
	v_lshl_add_u64 v[166:167], v[220:221], 0, s[92:93]
	s_add_i32 m0, s10, 0x2000
	s_nop 0
	global_load_lds_dwordx4 v[166:167], off
	v_lshl_add_u64 v[166:167], v[248:249], 0, s[92:93]
	s_mov_b32 m0, s56
	s_nop 0
	global_load_lds_dwordx4 v[166:167], off
	v_lshl_add_u64 v[166:167], v[250:251], 0, s[92:93]
	s_mov_b32 m0, s57
	s_nop 0
	global_load_lds_dwordx4 v[166:167], off
	s_waitcnt vmcnt(8)
	s_waitcnt lgkmcnt(0)
	s_barrier
	s_setprio 1
	s_waitcnt lgkmcnt(0)
	v_mfma_f32_16x16x32_bf16 v[56:59], v[146:149], v[192:195], v[56:59]
	v_lshrrev_b32_e32 v171, 8, v170
	v_and_b32_e32 v234, 15, v170
	v_lshl_add_u32 v171, v171, 6, v234
	s_lshl_b32 s98, s64, 8
	v_add_u32_e32 v171, s98, v171
	v_mul_lo_u32 v171, v171, s28
	v_bfe_u32 v234, v170, 6, 2
	v_bfe_u32 v224, v170, 4, 2
	v_mfma_f32_16x16x32_bf16 v[48:51], v[158:161], v[192:195], v[48:51]
	v_lshlrev_b32_e32 v234, 5, v234
	v_lshl_or_b32 v234, v224, 3, v234
	s_lshl_b32 s98, s63, 7
	v_add_u32_e32 v234, s98, v234
	v_add_lshl_u32 v232, v171, v234, 1
	v_mov_b32_e32 v233, 0
	v_lshl_add_u64 v[232:233], v[232:233], 0, s[30:31]
	s_lshl_b32 s98, s28, 5
	v_mfma_f32_16x16x32_bf16 v[40:43], v[146:149], v[200:203], v[40:43]
	s_mov_b32 s99, 0
	s_mov_b32 s100, 0xbfb8aa3b
	s_mov_b32 s101, 0xbfb8aa3b
	v_pk_mul_f32 v[120:121], v[120:121], v[172:173] op_sel_hi:[1,0]
	v_pk_mul_f32 v[122:123], v[122:123], v[172:173] op_sel_hi:[1,0]
	v_pk_mul_f32 v[124:125], v[124:125], v[172:173] op_sel_hi:[1,0]
	v_pk_mul_f32 v[126:127], v[126:127], v[172:173] op_sel_hi:[1,0]
	v_pk_mul_f32 v[224:225], v[120:121], s[100:101]
	v_mfma_f32_16x16x32_bf16 v[32:35], v[158:161], v[200:203], v[32:35]
	v_pk_mul_f32 v[228:229], v[122:123], s[100:101]
	v_exp_f32_e32 v224, v224
	v_exp_f32_e32 v225, v225
	v_exp_f32_e32 v228, v228
	v_exp_f32_e32 v229, v229
	v_add_f32_e32 v224, 1.0, v224
	v_add_f32_e32 v225, 1.0, v225
	v_add_f32_e32 v228, 1.0, v228
	v_mfma_f32_16x16x32_bf16 v[24:27], v[146:149], v[208:211], v[24:27]
	v_add_f32_e32 v229, 1.0, v229
	v_rcp_f32_e32 v224, v224
	v_rcp_f32_e32 v225, v225
	v_rcp_f32_e32 v228, v228
	v_rcp_f32_e32 v229, v229
	v_nop
	v_pk_mul_f32 v[120:121], v[120:121], v[224:225]
	v_pk_mul_f32 v[122:123], v[122:123], v[228:229]
	v_mfma_f32_16x16x32_bf16 v[16:19], v[158:161], v[208:211], v[16:19]
	v_pk_mul_f32 v[120:121], v[120:121], v[124:125]
	v_pk_mul_f32 v[122:123], v[122:123], v[126:127]
	v_pk_mul_f32 v[112:113], v[112:113], v[172:173] op_sel_hi:[1,0]
	v_pk_mul_f32 v[114:115], v[114:115], v[172:173] op_sel_hi:[1,0]
	v_pk_mul_f32 v[116:117], v[116:117], v[172:173] op_sel_hi:[1,0]
	v_pk_mul_f32 v[118:119], v[118:119], v[172:173] op_sel_hi:[1,0]
	v_pk_mul_f32 v[224:225], v[112:113], s[100:101]
	v_pk_mul_f32 v[228:229], v[114:115], s[100:101]
	v_mfma_f32_16x16x32_bf16 v[8:11], v[146:149], v[216:219], v[8:11]
	v_exp_f32_e32 v224, v224
	v_exp_f32_e32 v225, v225
	v_exp_f32_e32 v228, v228
	v_exp_f32_e32 v229, v229
	v_add_f32_e32 v224, 1.0, v224
	v_add_f32_e32 v225, 1.0, v225
	v_add_f32_e32 v228, 1.0, v228
	v_add_f32_e32 v229, 1.0, v229
	v_mfma_f32_16x16x32_bf16 v[4:7], v[158:161], v[216:219], v[4:7]
	v_rcp_f32_e32 v224, v224
	v_rcp_f32_e32 v225, v225
	v_rcp_f32_e32 v228, v228
	v_rcp_f32_e32 v229, v229
	v_nop
	v_pk_mul_f32 v[112:113], v[112:113], v[224:225]
	v_pk_mul_f32 v[114:115], v[114:115], v[228:229]
	v_pk_mul_f32 v[112:113], v[112:113], v[116:117]
	v_mfma_f32_16x16x32_bf16 v[56:59], v[154:157], v[196:199], v[56:59]
	v_pk_mul_f32 v[114:115], v[114:115], v[118:119]
	v_cvt_pk_bf16_f32 v120, v120, v121
	v_cvt_pk_bf16_f32 v121, v122, v123
	v_cvt_pk_bf16_f32 v122, v112, v113
	v_cvt_pk_bf16_f32 v123, v114, v115
	global_store_dwordx4 v[232:233], v[120:123], off
	v_lshl_add_u64 v[232:233], v[232:233], 0, s[98:99]
	v_pk_mul_f32 v[104:105], v[104:105], v[172:173] op_sel:[0,1]
	v_mfma_f32_16x16x32_bf16 v[48:51], v[162:165], v[196:199], v[48:51]
	v_pk_mul_f32 v[106:107], v[106:107], v[172:173] op_sel:[0,1]
	v_pk_mul_f32 v[108:109], v[108:109], v[172:173] op_sel:[0,1]
	v_pk_mul_f32 v[110:111], v[110:111], v[172:173] op_sel:[0,1]
	v_pk_mul_f32 v[224:225], v[104:105], s[100:101]
	v_pk_mul_f32 v[228:229], v[106:107], s[100:101]
	v_exp_f32_e32 v224, v224
	v_exp_f32_e32 v225, v225
	v_exp_f32_e32 v228, v228
	v_mfma_f32_16x16x32_bf16 v[40:43], v[154:157], v[204:207], v[40:43]
	v_exp_f32_e32 v229, v229
	v_add_f32_e32 v224, 1.0, v224
	v_add_f32_e32 v225, 1.0, v225
	v_add_f32_e32 v228, 1.0, v228
	v_add_f32_e32 v229, 1.0, v229
	v_rcp_f32_e32 v224, v224
	v_rcp_f32_e32 v225, v225
	v_rcp_f32_e32 v228, v228
	v_mfma_f32_16x16x32_bf16 v[32:35], v[162:165], v[204:207], v[32:35]
	v_rcp_f32_e32 v229, v229
	v_nop
	v_pk_mul_f32 v[104:105], v[104:105], v[224:225]
	v_pk_mul_f32 v[106:107], v[106:107], v[228:229]
	v_pk_mul_f32 v[104:105], v[104:105], v[108:109]
	v_pk_mul_f32 v[106:107], v[106:107], v[110:111]
	v_pk_mul_f32 v[96:97], v[96:97], v[172:173] op_sel:[0,1]
	v_pk_mul_f32 v[98:99], v[98:99], v[172:173] op_sel:[0,1]
; __device__ __forceinline__ unsigned cvt_pk_bf16(float lo, float hi) { unsigned r; asm volatile("v_cvt_pk_bf16_f32 %0, %1, %2" : "=v"(r) : "v"(lo), "v"(hi)); return r; }
; __device__ __forceinline__ float siluf_(float x) { return x * sigmoidf_(x); }
; #define PG8_MMA(ai, bj, At, Bt) do { __builtin_amdgcn_s_setprio(1); _Pragma("unroll") for (int k = 0; k < 2; ++k) _Pragma("unroll") for (int m = 0; m < 4; ++m) _Pragma("unroll") for (int n = 0; n < 2; ++n) \
;         acc[ai][bj][m][n] = __builtin_amdgcn_mfma_f32_16x16x32_bf16(Bt[n][k], At[m][k], acc[ai][bj][m][n], 0, 0, 0); __builtin_amdgcn_s_setprio(0); } while (0)
; #define PG8_WAIT_V(n) asm volatile("s_waitcnt vmcnt(" #n ")" ::: "memory")
; #define PG8_WAIT_L(n) asm volatile("s_waitcnt lgkmcnt(" #n ")" ::: "memory")
; #define PG8_BAR __builtin_amdgcn_s_barrier()
; #define PG8_SCHED __builtin_amdgcn_sched_barrier(0)
;     __device__ __forceinline__ void operator()(const f32x4 (&acc)[2][2][4][2], const Unit& u, int wr, int wc, int fr, int fq) const {
;     ...
;             for (int m = 0; m < 4; ++m) { const int row = row0 + ai * HALF + m * 16; bf16_t* rowp = O + (size_t)row * ldc + col0; const float rs = rsv[ai][m];
;                 f32x4 v0, v1;
; #pragma unroll
;                 for (int j = 0; j < 4; ++j) { v0[j] = siluf_(acc[ai][0][m][0][j] * rs) * (acc[ai][1][m][0][j] * rs); v1[j] = siluf_(acc[ai][0][m][1][j] * rs) * (acc[ai][1][m][1][j] * rs); }
;                 u32x4 w; w.x = cvt_pk_bf16(v0[0], v0[1]); w.y = cvt_pk_bf16(v0[2], v0[3]); w.z = cvt_pk_bf16(v1[0], v1[1]); w.w = cvt_pk_bf16(v1[2], v1[3]);
;                 *(u32x4*)rowp = w; }
; template <class Epi, bool ALIGN_EPI>
; __device__ __forceinline__ void gemm_phase(LAS unsigned char* lds, const Gemm g, const StaticOrder& S, const Epi& E, const int tid) {
;     ...
;             PG8_WAIT_V(8); PG8_WAIT_L(0); PG8_BAR; PG8_MMA(1, 0, At, B0); PG8_MMA(1, 1, At, B1); PG8_BAR; PG8_SCHED;
	v_mfma_f32_16x16x32_bf16 v[24:27], v[154:157], v[212:215], v[24:27]
	v_pk_mul_f32 v[100:101], v[100:101], v[172:173] op_sel:[0,1]
	v_pk_mul_f32 v[102:103], v[102:103], v[172:173] op_sel:[0,1]
	v_pk_mul_f32 v[224:225], v[96:97], s[100:101]
	v_pk_mul_f32 v[228:229], v[98:99], s[100:101]
	v_exp_f32_e32 v224, v224
	v_exp_f32_e32 v225, v225
	v_exp_f32_e32 v228, v228
	v_exp_f32_e32 v229, v229
	v_mfma_f32_16x16x32_bf16 v[16:19], v[162:165], v[212:215], v[16:19]
	v_add_f32_e32 v224, 1.0, v224
	v_add_f32_e32 v225, 1.0, v225
	v_add_f32_e32 v228, 1.0, v228
	v_add_f32_e32 v229, 1.0, v229
	v_rcp_f32_e32 v224, v224
	v_rcp_f32_e32 v225, v225
	v_rcp_f32_e32 v228, v228
	v_rcp_f32_e32 v229, v229
	v_mfma_f32_16x16x32_bf16 v[8:11], v[154:157], v[240:243], v[8:11]
	v_nop
	v_pk_mul_f32 v[96:97], v[96:97], v[224:225]
	v_pk_mul_f32 v[98:99], v[98:99], v[228:229]
	v_pk_mul_f32 v[96:97], v[96:97], v[100:101]
	v_pk_mul_f32 v[98:99], v[98:99], v[102:103]
	v_cvt_pk_bf16_f32 v104, v104, v105
	v_cvt_pk_bf16_f32 v105, v106, v107
	v_cvt_pk_bf16_f32 v106, v96, v97
	v_mfma_f32_16x16x32_bf16 v[4:7], v[162:165], v[240:243], v[4:7]
	v_cvt_pk_bf16_f32 v107, v98, v99
	global_store_dwordx4 v[232:233], v[104:107], off
	v_lshl_add_u64 v[232:233], v[232:233], 0, s[98:99]
	v_pk_mul_f32 v[88:89], v[88:89], v[236:237] op_sel_hi:[1,0]
	v_pk_mul_f32 v[90:91], v[90:91], v[236:237] op_sel_hi:[1,0]
	v_pk_mul_f32 v[92:93], v[92:93], v[236:237] op_sel_hi:[1,0]
	v_pk_mul_f32 v[94:95], v[94:95], v[236:237] op_sel_hi:[1,0]
	v_pk_mul_f32 v[224:225], v[88:89], s[100:101]
	s_setprio 0
	s_setprio 1
	v_mfma_f32_16x16x32_bf16 v[60:63], v[176:179], v[192:195], v[60:63]
	v_pk_mul_f32 v[228:229], v[90:91], s[100:101]
	v_exp_f32_e32 v224, v224
	v_exp_f32_e32 v225, v225
	v_exp_f32_e32 v228, v228
	v_exp_f32_e32 v229, v229
	v_add_f32_e32 v224, 1.0, v224
	v_add_f32_e32 v225, 1.0, v225
	v_add_f32_e32 v228, 1.0, v228
	v_mfma_f32_16x16x32_bf16 v[52:55], v[184:187], v[192:195], v[52:55]
	v_add_f32_e32 v229, 1.0, v229
	v_rcp_f32_e32 v224, v224
	v_rcp_f32_e32 v225, v225
	v_rcp_f32_e32 v228, v228
	v_rcp_f32_e32 v229, v229
	v_nop
	v_pk_mul_f32 v[88:89], v[88:89], v[224:225]
	v_pk_mul_f32 v[90:91], v[90:91], v[228:229]
	v_mfma_f32_16x16x32_bf16 v[44:47], v[176:179], v[200:203], v[44:47]
	v_pk_mul_f32 v[88:89], v[88:89], v[92:93]
	v_pk_mul_f32 v[90:91], v[90:91], v[94:95]
	v_pk_mul_f32 v[80:81], v[80:81], v[236:237] op_sel_hi:[1,0]
	v_pk_mul_f32 v[82:83], v[82:83], v[236:237] op_sel_hi:[1,0]
	v_pk_mul_f32 v[84:85], v[84:85], v[236:237] op_sel_hi:[1,0]
	v_pk_mul_f32 v[86:87], v[86:87], v[236:237] op_sel_hi:[1,0]
	v_pk_mul_f32 v[224:225], v[80:81], s[100:101]
	v_pk_mul_f32 v[228:229], v[82:83], s[100:101]
	v_mfma_f32_16x16x32_bf16 v[36:39], v[184:187], v[200:203], v[36:39]
	v_exp_f32_e32 v224, v224
	v_exp_f32_e32 v225, v225
	v_exp_f32_e32 v228, v228
	v_exp_f32_e32 v229, v229
	v_add_f32_e32 v224, 1.0, v224
	v_add_f32_e32 v225, 1.0, v225
	v_add_f32_e32 v228, 1.0, v228
	v_add_f32_e32 v229, 1.0, v229
	v_mfma_f32_16x16x32_bf16 v[28:31], v[176:179], v[208:211], v[28:31]
	v_rcp_f32_e32 v224, v224
	v_rcp_f32_e32 v225, v225
	v_rcp_f32_e32 v228, v228
	v_rcp_f32_e32 v229, v229
	v_nop
	v_pk_mul_f32 v[80:81], v[80:81], v[224:225]
	v_pk_mul_f32 v[82:83], v[82:83], v[228:229]
	v_pk_mul_f32 v[80:81], v[80:81], v[84:85]
	v_mfma_f32_16x16x32_bf16 v[20:23], v[184:187], v[208:211], v[20:23]
	v_pk_mul_f32 v[82:83], v[82:83], v[86:87]
	v_cvt_pk_bf16_f32 v88, v88, v89
	v_cvt_pk_bf16_f32 v89, v90, v91
	v_cvt_pk_bf16_f32 v90, v80, v81
	v_cvt_pk_bf16_f32 v91, v82, v83
	global_store_dwordx4 v[232:233], v[88:91], off
	v_lshl_add_u64 v[232:233], v[232:233], 0, s[98:99]
	v_pk_mul_f32 v[72:73], v[72:73], v[236:237] op_sel:[0,1]
	v_mfma_f32_16x16x32_bf16 v[12:15], v[176:179], v[216:219], v[12:15]
	v_pk_mul_f32 v[74:75], v[74:75], v[236:237] op_sel:[0,1]
	v_pk_mul_f32 v[76:77], v[76:77], v[236:237] op_sel:[0,1]
	v_pk_mul_f32 v[78:79], v[78:79], v[236:237] op_sel:[0,1]
	v_pk_mul_f32 v[224:225], v[72:73], s[100:101]
	v_pk_mul_f32 v[228:229], v[74:75], s[100:101]
	v_exp_f32_e32 v224, v224
	v_exp_f32_e32 v225, v225
	v_exp_f32_e32 v228, v228
	v_mfma_f32_16x16x32_bf16 v[0:3], v[184:187], v[216:219], v[0:3]
	v_exp_f32_e32 v229, v229
	v_add_f32_e32 v224, 1.0, v224
	v_add_f32_e32 v225, 1.0, v225
	v_add_f32_e32 v228, 1.0, v228
	v_add_f32_e32 v229, 1.0, v229
	v_rcp_f32_e32 v224, v224
	v_rcp_f32_e32 v225, v225
	v_rcp_f32_e32 v228, v228
	v_mfma_f32_16x16x32_bf16 v[60:63], v[180:183], v[196:199], v[60:63]
	v_rcp_f32_e32 v229, v229
	v_nop
	v_pk_mul_f32 v[72:73], v[72:73], v[224:225]
	v_pk_mul_f32 v[74:75], v[74:75], v[228:229]
	v_pk_mul_f32 v[72:73], v[72:73], v[76:77]
	v_pk_mul_f32 v[74:75], v[74:75], v[78:79]
	v_pk_mul_f32 v[64:65], v[64:65], v[236:237] op_sel:[0,1]
	v_pk_mul_f32 v[66:67], v[66:67], v[236:237] op_sel:[0,1]
	v_mfma_f32_16x16x32_bf16 v[52:55], v[188:191], v[196:199], v[52:55]
	v_pk_mul_f32 v[68:69], v[68:69], v[236:237] op_sel:[0,1]
	v_pk_mul_f32 v[70:71], v[70:71], v[236:237] op_sel:[0,1]
	v_pk_mul_f32 v[224:225], v[64:65], s[100:101]
	v_pk_mul_f32 v[228:229], v[66:67], s[100:101]
	v_exp_f32_e32 v224, v224
	v_exp_f32_e32 v225, v225
	v_exp_f32_e32 v228, v228
	v_exp_f32_e32 v229, v229
	v_mfma_f32_16x16x32_bf16 v[44:47], v[180:183], v[204:207], v[44:47]
	v_add_f32_e32 v224, 1.0, v224
	v_add_f32_e32 v225, 1.0, v225
	v_add_f32_e32 v228, 1.0, v228
	v_add_f32_e32 v229, 1.0, v229
	v_rcp_f32_e32 v224, v224
	v_rcp_f32_e32 v225, v225
	v_rcp_f32_e32 v228, v228
	v_rcp_f32_e32 v229, v229
	v_mfma_f32_16x16x32_bf16 v[36:39], v[188:191], v[204:207], v[36:39]
	v_nop
	v_pk_mul_f32 v[64:65], v[64:65], v[224:225]
	v_pk_mul_f32 v[66:67], v[66:67], v[228:229]
	v_pk_mul_f32 v[64:65], v[64:65], v[68:69]
	v_pk_mul_f32 v[66:67], v[66:67], v[70:71]
	v_cvt_pk_bf16_f32 v72, v72, v73
	v_cvt_pk_bf16_f32 v73, v74, v75
	v_cvt_pk_bf16_f32 v74, v64, v65
	v_mfma_f32_16x16x32_bf16 v[28:31], v[180:183], v[212:215], v[28:31]
	v_cvt_pk_bf16_f32 v75, v66, v67
	global_store_dwordx4 v[232:233], v[72:75], off
	v_lshl_add_u64 v[232:233], v[232:233], 0, s[98:99]
	v_lshl_add_u64 v[232:233], v[232:233], 0, s[98:99]
	v_lshl_add_u64 v[232:233], v[232:233], 0, s[98:99]
	v_lshl_add_u64 v[232:233], v[232:233], 0, s[98:99]
	v_lshl_add_u64 v[232:233], v[232:233], 0, s[98:99]
	v_mfma_f32_16x16x32_bf16 v[20:23], v[188:191], v[212:215], v[20:23]
	v_mfma_f32_16x16x32_bf16 v[12:15], v[180:183], v[240:243], v[12:15]
	v_mfma_f32_16x16x32_bf16 v[0:3], v[188:191], v[240:243], v[0:3]
	s_setprio 0
	s_barrier
	v_lshl_add_u64 v[142:143], v[142:143], 0, s[80:81]
	v_lshl_add_u64 v[144:145], v[144:145], 0, s[80:81]

; __device__ __forceinline__ unsigned cvt_pk_bf16(float lo, float hi) { unsigned r; asm volatile("v_cvt_pk_bf16_f32 %0, %1, %2" : "=v"(r) : "v"(lo), "v"(hi)); return r; }
; __device__ __forceinline__ float siluf_(float x) { return x * sigmoidf_(x); }
;     __device__ __forceinline__ void operator()(const f32x4 (&acc)[2][2][4][2], const Unit& u, int wr, int wc, int fr, int fq) const {
;     ...
;         for (int ai = 0; ai < 2; ++ai)
; #pragma unroll
;             for (int m = 0; m < 4; ++m) { const int row = row0 + ai * HALF + m * 16; bf16_t* rowp = O + (size_t)row * ldc + col0; const float rs = rsv[ai][m];
;                 f32x4 v0, v1;
; #pragma unroll
;                 for (int j = 0; j < 4; ++j) { v0[j] = siluf_(acc[ai][0][m][0][j] * rs) * (acc[ai][1][m][0][j] * rs); v1[j] = siluf_(acc[ai][0][m][1][j] * rs) * (acc[ai][1][m][1][j] * rs); }
;                 u32x4 w; w.x = cvt_pk_bf16(v0[0], v0[1]); w.y = cvt_pk_bf16(v0[2], v0[3]); w.z = cvt_pk_bf16(v1[0], v1[1]); w.w = cvt_pk_bf16(v1[2], v1[3]);
;                 *(u32x4*)rowp = w; }
.LBB0_311:
	s_nop 7
	s_lshl_b32 s98, s28, 5
	s_mov_b32 s99, 0
	s_mov_b32 s100, 0xbfb8aa3b
	s_mov_b32 s101, 0xbfb8aa3b
	v_pk_mul_f32 v[56:57], v[56:57], v[238:239] op_sel_hi:[1,0]
	v_pk_mul_f32 v[58:59], v[58:59], v[238:239] op_sel_hi:[1,0]
	v_pk_mul_f32 v[60:61], v[60:61], v[238:239] op_sel_hi:[1,0]
	v_pk_mul_f32 v[62:63], v[62:63], v[238:239] op_sel_hi:[1,0]
	v_pk_mul_f32 v[224:225], v[56:57], s[100:101]
	v_pk_mul_f32 v[228:229], v[58:59], s[100:101]
	v_exp_f32_e32 v224, v224
	v_exp_f32_e32 v225, v225
	v_exp_f32_e32 v228, v228
	v_exp_f32_e32 v229, v229
	v_add_f32_e32 v224, 1.0, v224
	v_add_f32_e32 v225, 1.0, v225
	v_add_f32_e32 v228, 1.0, v228
	v_add_f32_e32 v229, 1.0, v229
	v_rcp_f32_e32 v224, v224
	v_rcp_f32_e32 v225, v225
	v_rcp_f32_e32 v228, v228
	v_rcp_f32_e32 v229, v229
	v_nop
	v_pk_mul_f32 v[56:57], v[56:57], v[224:225]
	v_pk_mul_f32 v[58:59], v[58:59], v[228:229]
	v_pk_mul_f32 v[56:57], v[56:57], v[60:61]
	v_pk_mul_f32 v[58:59], v[58:59], v[62:63]
	v_pk_mul_f32 v[48:49], v[48:49], v[238:239] op_sel_hi:[1,0]
	v_pk_mul_f32 v[50:51], v[50:51], v[238:239] op_sel_hi:[1,0]
	v_pk_mul_f32 v[52:53], v[52:53], v[238:239] op_sel_hi:[1,0]
	v_pk_mul_f32 v[54:55], v[54:55], v[238:239] op_sel_hi:[1,0]
	v_pk_mul_f32 v[224:225], v[48:49], s[100:101]
	v_pk_mul_f32 v[228:229], v[50:51], s[100:101]
	v_exp_f32_e32 v224, v224
	v_exp_f32_e32 v225, v225
	v_exp_f32_e32 v228, v228
	v_exp_f32_e32 v229, v229
	v_add_f32_e32 v224, 1.0, v224
	v_add_f32_e32 v225, 1.0, v225
	v_add_f32_e32 v228, 1.0, v228
	v_add_f32_e32 v229, 1.0, v229
	v_rcp_f32_e32 v224, v224
	v_rcp_f32_e32 v225, v225
	v_rcp_f32_e32 v228, v228
	v_rcp_f32_e32 v229, v229
	v_nop
	v_pk_mul_f32 v[48:49], v[48:49], v[224:225]
	v_pk_mul_f32 v[50:51], v[50:51], v[228:229]
	v_pk_mul_f32 v[48:49], v[48:49], v[52:53]
	v_pk_mul_f32 v[50:51], v[50:51], v[54:55]
	v_cvt_pk_bf16_f32 v56, v56, v57
	v_cvt_pk_bf16_f32 v57, v58, v59
	v_cvt_pk_bf16_f32 v58, v48, v49
	v_cvt_pk_bf16_f32 v59, v50, v51
	global_store_dwordx4 v[232:233], v[56:59], off
	v_lshl_add_u64 v[232:233], v[232:233], 0, s[98:99]
	v_pk_mul_f32 v[40:41], v[40:41], v[238:239] op_sel:[0,1]
	v_pk_mul_f32 v[42:43], v[42:43], v[238:239] op_sel:[0,1]
	v_pk_mul_f32 v[44:45], v[44:45], v[238:239] op_sel:[0,1]
	v_pk_mul_f32 v[46:47], v[46:47], v[238:239] op_sel:[0,1]
	v_pk_mul_f32 v[224:225], v[40:41], s[100:101]
	v_pk_mul_f32 v[228:229], v[42:43], s[100:101]
	v_exp_f32_e32 v224, v224
	v_exp_f32_e32 v225, v225
	v_exp_f32_e32 v228, v228
	v_exp_f32_e32 v229, v229
	v_add_f32_e32 v224, 1.0, v224
	v_add_f32_e32 v225, 1.0, v225
	v_add_f32_e32 v228, 1.0, v228
	v_add_f32_e32 v229, 1.0, v229
	v_rcp_f32_e32 v224, v224
	v_rcp_f32_e32 v225, v225
	v_rcp_f32_e32 v228, v228
	v_rcp_f32_e32 v229, v229
	v_nop
	v_pk_mul_f32 v[40:41], v[40:41], v[224:225]
	v_pk_mul_f32 v[42:43], v[42:43], v[228:229]
	v_pk_mul_f32 v[40:41], v[40:41], v[44:45]
	v_pk_mul_f32 v[42:43], v[42:43], v[46:47]
	v_pk_mul_f32 v[32:33], v[32:33], v[238:239] op_sel:[0,1]
	v_pk_mul_f32 v[34:35], v[34:35], v[238:239] op_sel:[0,1]
	v_pk_mul_f32 v[36:37], v[36:37], v[238:239] op_sel:[0,1]
	v_pk_mul_f32 v[38:39], v[38:39], v[238:239] op_sel:[0,1]
	v_pk_mul_f32 v[224:225], v[32:33], s[100:101]
	v_pk_mul_f32 v[228:229], v[34:35], s[100:101]
	v_exp_f32_e32 v224, v224
	v_exp_f32_e32 v225, v225
	v_exp_f32_e32 v228, v228
	v_exp_f32_e32 v229, v229
	v_add_f32_e32 v224, 1.0, v224
	v_add_f32_e32 v225, 1.0, v225
	v_add_f32_e32 v228, 1.0, v228
	v_add_f32_e32 v229, 1.0, v229
	v_rcp_f32_e32 v224, v224
	v_rcp_f32_e32 v225, v225
	v_rcp_f32_e32 v228, v228
	v_rcp_f32_e32 v229, v229
	v_nop
	v_pk_mul_f32 v[32:33], v[32:33], v[224:225]
	v_pk_mul_f32 v[34:35], v[34:35], v[228:229]
	v_pk_mul_f32 v[32:33], v[32:33], v[36:37]
	v_pk_mul_f32 v[34:35], v[34:35], v[38:39]
	v_cvt_pk_bf16_f32 v40, v40, v41
	v_cvt_pk_bf16_f32 v41, v42, v43
	v_cvt_pk_bf16_f32 v42, v32, v33
	v_cvt_pk_bf16_f32 v43, v34, v35
	global_store_dwordx4 v[232:233], v[40:43], off
	v_lshl_add_u64 v[232:233], v[232:233], 0, s[98:99]
	v_pk_mul_f32 v[24:25], v[24:25], v[230:231] op_sel_hi:[1,0]
	v_pk_mul_f32 v[26:27], v[26:27], v[230:231] op_sel_hi:[1,0]
	v_pk_mul_f32 v[28:29], v[28:29], v[230:231] op_sel_hi:[1,0]
	v_pk_mul_f32 v[30:31], v[30:31], v[230:231] op_sel_hi:[1,0]
	v_pk_mul_f32 v[224:225], v[24:25], s[100:101]
; __device__ __forceinline__ unsigned cvt_pk_bf16(float lo, float hi) { unsigned r; asm volatile("v_cvt_pk_bf16_f32 %0, %1, %2" : "=v"(r) : "v"(lo), "v"(hi)); return r; }
; __device__ __forceinline__ float siluf_(float x) { return x * sigmoidf_(x); }
;     __device__ __forceinline__ void operator()(const f32x4 (&acc)[2][2][4][2], const Unit& u, int wr, int wc, int fr, int fq) const {
;     ...
;         for (int ai = 0; ai < 2; ++ai)
; #pragma unroll
;             for (int m = 0; m < 4; ++m) { const int row = row0 + ai * HALF + m * 16; bf16_t* rowp = O + (size_t)row * ldc + col0; const float rs = rsv[ai][m];
;                 f32x4 v0, v1;
; #pragma unroll
;                 for (int j = 0; j < 4; ++j) { v0[j] = siluf_(acc[ai][0][m][0][j] * rs) * (acc[ai][1][m][0][j] * rs); v1[j] = siluf_(acc[ai][0][m][1][j] * rs) * (acc[ai][1][m][1][j] * rs); }
;                 u32x4 w; w.x = cvt_pk_bf16(v0[0], v0[1]); w.y = cvt_pk_bf16(v0[2], v0[3]); w.z = cvt_pk_bf16(v1[0], v1[1]); w.w = cvt_pk_bf16(v1[2], v1[3]);
;                 *(u32x4*)rowp = w; }
	v_pk_mul_f32 v[228:229], v[26:27], s[100:101]
	v_exp_f32_e32 v224, v224
	v_exp_f32_e32 v225, v225
	v_exp_f32_e32 v228, v228
	v_exp_f32_e32 v229, v229
	v_add_f32_e32 v224, 1.0, v224
	v_add_f32_e32 v225, 1.0, v225
	v_add_f32_e32 v228, 1.0, v228
	v_add_f32_e32 v229, 1.0, v229
	v_rcp_f32_e32 v224, v224
	v_rcp_f32_e32 v225, v225
	v_rcp_f32_e32 v228, v228
	v_rcp_f32_e32 v229, v229
	v_nop
	v_pk_mul_f32 v[24:25], v[24:25], v[224:225]
	v_pk_mul_f32 v[26:27], v[26:27], v[228:229]
	v_pk_mul_f32 v[24:25], v[24:25], v[28:29]
	v_pk_mul_f32 v[26:27], v[26:27], v[30:31]
	v_pk_mul_f32 v[16:17], v[16:17], v[230:231] op_sel_hi:[1,0]
	v_pk_mul_f32 v[18:19], v[18:19], v[230:231] op_sel_hi:[1,0]
	v_pk_mul_f32 v[20:21], v[20:21], v[230:231] op_sel_hi:[1,0]
	v_pk_mul_f32 v[22:23], v[22:23], v[230:231] op_sel_hi:[1,0]
	v_pk_mul_f32 v[224:225], v[16:17], s[100:101]
	v_pk_mul_f32 v[228:229], v[18:19], s[100:101]
	v_exp_f32_e32 v224, v224
	v_exp_f32_e32 v225, v225
	v_exp_f32_e32 v228, v228
	v_exp_f32_e32 v229, v229
	v_add_f32_e32 v224, 1.0, v224
	v_add_f32_e32 v225, 1.0, v225
	v_add_f32_e32 v228, 1.0, v228
	v_add_f32_e32 v229, 1.0, v229
	v_rcp_f32_e32 v224, v224
	v_rcp_f32_e32 v225, v225
	v_rcp_f32_e32 v228, v228
	v_rcp_f32_e32 v229, v229
	v_nop
	v_pk_mul_f32 v[16:17], v[16:17], v[224:225]
	v_pk_mul_f32 v[18:19], v[18:19], v[228:229]
	v_pk_mul_f32 v[16:17], v[16:17], v[20:21]
	v_pk_mul_f32 v[18:19], v[18:19], v[22:23]
	v_cvt_pk_bf16_f32 v24, v24, v25
	v_cvt_pk_bf16_f32 v25, v26, v27
	v_cvt_pk_bf16_f32 v26, v16, v17
	v_cvt_pk_bf16_f32 v27, v18, v19
	global_store_dwordx4 v[232:233], v[24:27], off
	v_lshl_add_u64 v[232:233], v[232:233], 0, s[98:99]
	v_pk_mul_f32 v[8:9], v[8:9], v[230:231] op_sel:[0,1]
	v_pk_mul_f32 v[10:11], v[10:11], v[230:231] op_sel:[0,1]
	v_pk_mul_f32 v[12:13], v[12:13], v[230:231] op_sel:[0,1]
	v_pk_mul_f32 v[14:15], v[14:15], v[230:231] op_sel:[0,1]
	v_pk_mul_f32 v[224:225], v[8:9], s[100:101]
	v_pk_mul_f32 v[228:229], v[10:11], s[100:101]
	v_exp_f32_e32 v224, v224
	v_exp_f32_e32 v225, v225
	v_exp_f32_e32 v228, v228
	v_exp_f32_e32 v229, v229
	v_add_f32_e32 v224, 1.0, v224
	v_add_f32_e32 v225, 1.0, v225
	v_add_f32_e32 v228, 1.0, v228
	v_add_f32_e32 v229, 1.0, v229
	v_rcp_f32_e32 v224, v224
	v_rcp_f32_e32 v225, v225
	v_rcp_f32_e32 v228, v228
	v_rcp_f32_e32 v229, v229
	v_nop
	v_pk_mul_f32 v[8:9], v[8:9], v[224:225]
	v_pk_mul_f32 v[10:11], v[10:11], v[228:229]
	v_pk_mul_f32 v[8:9], v[8:9], v[12:13]
	v_pk_mul_f32 v[10:11], v[10:11], v[14:15]
	v_pk_mul_f32 v[4:5], v[4:5], v[230:231] op_sel:[0,1]
	v_pk_mul_f32 v[6:7], v[6:7], v[230:231] op_sel:[0,1]
	v_pk_mul_f32 v[0:1], v[0:1], v[230:231] op_sel:[0,1]
	v_pk_mul_f32 v[2:3], v[2:3], v[230:231] op_sel:[0,1]
	v_pk_mul_f32 v[224:225], v[4:5], s[100:101]
	v_pk_mul_f32 v[228:229], v[6:7], s[100:101]
	v_exp_f32_e32 v224, v224
	v_exp_f32_e32 v225, v225
	v_exp_f32_e32 v228, v228
	v_exp_f32_e32 v229, v229
	v_add_f32_e32 v224, 1.0, v224
	v_add_f32_e32 v225, 1.0, v225
	v_add_f32_e32 v228, 1.0, v228
	v_add_f32_e32 v229, 1.0, v229
	v_rcp_f32_e32 v224, v224
	v_rcp_f32_e32 v225, v225
	v_rcp_f32_e32 v228, v228
	v_rcp_f32_e32 v229, v229
	v_nop
	v_pk_mul_f32 v[4:5], v[4:5], v[224:225]
	v_pk_mul_f32 v[6:7], v[6:7], v[228:229]
	v_pk_mul_f32 v[4:5], v[4:5], v[0:1]
	v_pk_mul_f32 v[6:7], v[6:7], v[2:3]
	v_cvt_pk_bf16_f32 v8, v8, v9
	v_cvt_pk_bf16_f32 v9, v10, v11
	v_cvt_pk_bf16_f32 v10, v4, v5
	v_cvt_pk_bf16_f32 v11, v6, v7
	global_store_dwordx4 v[232:233], v[8:11], off
	s_mov_b64 s[10:11], -1
	s_and_b64 vcc, exec, s[8:9]
	s_cbranch_vccnz .LBB0_299
	s_andn2_b64 vcc, exec, s[40:41]
	s_cbranch_vccnz .LBB0_298
	s_barrier
	s_branch .LBB0_298
.LBB0_314:
	v_mbcnt_lo_u32_b32 v225, -1, 0
	v_mbcnt_hi_u32_b32 v225, -1, v225
	v_mov_b32_e32 v224, 0x260
	v_and_b32_e32 v228, 64, v225
	v_add_u32_e32 v228, 64, v228
	v_xor_b32_e32 v229, 1, v225
	v_xor_b32_e32 v230, 2, v225
	v_xor_b32_e32 v231, 4, v225
	v_xor_b32_e32 v232, 8, v225
	v_xor_b32_e32 v233, 16, v225
	v_xor_b32_e32 v234, 32, v225
	v_mov_b32_e32 v236, 0xf149f2ca
	v_mov_b32_e32 v238, 0xfffff
	s_waitcnt vmcnt(0)
	v_readlane_b32 s60, v255, 51
	s_mov_b32 s52, 0x30000
	s_movk_i32 s53, 0x2400
	s_mov_b32 s54, 0xf149f2ca
	s_mov_b64 s[56:57], 0x100000
	s_mov_b64 s[58:59], 0xfffff
	v_readlane_b32 s61, v255, 52
	s_barrier
